# plus RWKV scan steps rebalanced across tile barriers 6/5/5 -> 7/3/6
# baseline (speedup 1.0000x reference)
.LBB0_595:
	s_andn2_saveexec_b64 s[0:1], s[20:21]
	s_cbranch_execz .LBB0_609
	s_bitcmp1_b32 s25, 0
	s_cselect_b32 s20, 0x6000, 0
	v_add_u32_e32 v1, s20, v143
	ds_read_b128 v[32:35], v1
	ds_read_b128 v[40:43], v1 offset:16
	s_and_b32 s20, s25, 1
	s_mul_i32 s21, s20, 0x6000
	s_add_i32 s21, s21, 0
	s_waitcnt lgkmcnt(1)
	v_pk_mul_f32 v[2:3], v[66:67], v[34:35] op_sel_hi:[1,0]
	v_pk_mul_f32 v[34:35], v[64:65], v[34:35] op_sel:[0,1]
	v_pk_fma_f32 v[2:3], v[70:71], v[32:33], v[2:3] op_sel_hi:[1,0,1]
	v_pk_fma_f32 v[32:33], v[68:69], v[32:33], v[34:35] op_sel:[0,1,0]
	s_waitcnt lgkmcnt(0)
	v_pk_fma_f32 v[2:3], v[62:63], v[40:41], v[2:3] op_sel_hi:[1,0,1]
	v_pk_fma_f32 v[32:33], v[60:61], v[40:41], v[32:33] op_sel:[0,1,0]
	v_pk_fma_f32 v[2:3], v[46:47], v[42:43], v[2:3] op_sel_hi:[1,0,1]
	v_pk_fma_f32 v[32:33], v[44:45], v[42:43], v[32:33] op_sel:[0,1,0]
	v_lshl_add_u32 v152, v97, 2, s21
	v_pk_add_f32 v[2:3], v[2:3], v[32:33]
	v_lshl_add_u32 v151, v98, 2, s21
	ds_read_b128 v[72:75], v152 offset:4096
	ds_read_b128 v[154:157], v152 offset:4112
	ds_read_b128 v[158:161], v152 offset:8192
	ds_read_b128 v[166:169], v152 offset:8208
	ds_read_b128 v[170:173], v152 offset:12288
	ds_read_b128 v[174:177], v152 offset:12304
	ds_read_b128 v[178:181], v152 offset:16384
	ds_read_b128 v[198:201], v152 offset:16400
	ds_read_b64 v[202:203], v151 offset:20480
	ds_read_b128 v[36:39], v1 offset:256
	ds_read_b128 v[28:31], v1 offset:272
	v_mov_b32_dpp v32, v2 quad_perm:[1,0,3,2] row_mask:0xf bank_mask:0xf bound_ctrl:1
	v_mov_b32_dpp v33, v3 quad_perm:[1,0,3,2] row_mask:0xf bank_mask:0xf bound_ctrl:1
	v_pk_add_f32 v[2:3], v[2:3], v[32:33]
	s_lshl_b32 s20, s20, 12
	v_add_u32_e32 v153, s20, v99
	v_mov_b32_dpp v32, v2 quad_perm:[2,3,0,1] row_mask:0xf bank_mask:0xf bound_ctrl:1
	v_mov_b32_dpp v33, v3 quad_perm:[2,3,0,1] row_mask:0xf bank_mask:0xf bound_ctrl:1
	v_pk_add_f32 v[2:3], v[2:3], v[32:33]
	s_nop 1
	v_mov_b32_dpp v32, v2 row_half_mirror row_mask:0xf bank_mask:0xf bound_ctrl:1
	v_mov_b32_dpp v33, v3 row_half_mirror row_mask:0xf bank_mask:0xf bound_ctrl:1
	v_pk_add_f32 v[32:33], v[2:3], v[32:33]
	s_waitcnt lgkmcnt(8)
	v_pk_mul_f32 v[2:3], v[158:159], v[32:33] op_sel_hi:[0,1]
	s_waitcnt lgkmcnt(2)
	v_pk_fma_f32 v[2:3], v[170:171], v[202:203], v[2:3] op_sel_hi:[0,1,1] neg_lo:[0,0,1] neg_hi:[0,0,1]
	v_pk_mul_f32 v[34:35], v[158:159], v[32:33] op_sel:[1,0]
	v_pk_fma_f32 v[2:3], v[70:71], v[72:73], v[2:3] op_sel_hi:[1,0,1]
	v_pk_fma_f32 v[34:35], v[170:171], v[202:203], v[34:35] op_sel:[1,0,0] neg_lo:[0,0,1] neg_hi:[0,0,1]
	v_pk_mul_f32 v[42:43], v[160:161], v[32:33] op_sel_hi:[0,1]
	v_pk_fma_f32 v[68:69], v[68:69], v[72:73], v[34:35] op_sel:[0,1,0]
	v_pk_fma_f32 v[42:43], v[172:173], v[202:203], v[42:43] op_sel_hi:[0,1,1] neg_lo:[0,0,1] neg_hi:[0,0,1]
	v_pk_mul_f32 v[70:71], v[160:161], v[32:33] op_sel:[1,0]
	v_pk_fma_f32 v[66:67], v[66:67], v[74:75], v[42:43] op_sel_hi:[1,0,1]
	v_pk_fma_f32 v[70:71], v[172:173], v[202:203], v[70:71] op_sel:[1,0,0] neg_lo:[0,0,1] neg_hi:[0,0,1]
	v_pk_fma_f32 v[40:41], v[178:179], v[68:69], 0 op_sel:[1,0,0] op_sel_hi:[1,1,0]
	v_pk_fma_f32 v[64:65], v[64:65], v[74:75], v[70:71] op_sel:[0,1,0]
	v_pk_fma_f32 v[40:41], v[180:181], v[64:65], v[40:41] op_sel:[1,0,0]
	v_pk_mul_f32 v[42:43], v[166:167], v[32:33] op_sel_hi:[0,1]
	v_pk_fma_f32 v[42:43], v[174:175], v[202:203], v[42:43] op_sel_hi:[0,1,1] neg_lo:[0,0,1] neg_hi:[0,0,1]
	v_pk_fma_f32 v[62:63], v[62:63], v[154:155], v[42:43] op_sel_hi:[1,0,1]
	v_pk_mul_f32 v[42:43], v[166:167], v[32:33] op_sel:[1,0]
	v_pk_fma_f32 v[34:35], v[178:179], v[2:3], 0 op_sel_hi:[0,1,0]
	v_pk_fma_f32 v[42:43], v[174:175], v[202:203], v[42:43] op_sel:[1,0,0] neg_lo:[0,0,1] neg_hi:[0,0,1]
	v_pk_fma_f32 v[60:61], v[60:61], v[154:155], v[42:43] op_sel:[0,1,0]
	v_pk_mul_f32 v[42:43], v[168:169], v[32:33] op_sel_hi:[0,1]
	v_pk_fma_f32 v[34:35], v[180:181], v[66:67], v[34:35] op_sel_hi:[0,1,1]
	v_pk_fma_f32 v[42:43], v[176:177], v[202:203], v[42:43] op_sel_hi:[0,1,1] neg_lo:[0,0,1] neg_hi:[0,0,1]
	v_pk_mul_f32 v[32:33], v[168:169], v[32:33] op_sel:[1,0]
	v_pk_fma_f32 v[34:35], v[198:199], v[62:63], v[34:35] op_sel_hi:[0,1,1]
	v_pk_fma_f32 v[46:47], v[46:47], v[156:157], v[42:43] op_sel_hi:[1,0,1]
	v_pk_fma_f32 v[32:33], v[176:177], v[202:203], v[32:33] op_sel:[1,0,0] neg_lo:[0,0,1] neg_hi:[0,0,1]
	v_pk_fma_f32 v[40:41], v[198:199], v[60:61], v[40:41] op_sel:[1,0,0]
	v_pk_fma_f32 v[44:45], v[44:45], v[156:157], v[32:33] op_sel:[0,1,0]
	v_pk_fma_f32 v[32:33], v[200:201], v[46:47], v[34:35] op_sel_hi:[0,1,1]
	v_pk_fma_f32 v[34:35], v[200:201], v[44:45], v[40:41] op_sel:[1,0,0]
	v_pk_add_f32 v[32:33], v[32:33], v[34:35]
	s_nop 1
	v_mov_b32_dpp v34, v32 quad_perm:[1,0,3,2] row_mask:0xf bank_mask:0xf bound_ctrl:1
	v_mov_b32_dpp v35, v33 quad_perm:[1,0,3,2] row_mask:0xf bank_mask:0xf bound_ctrl:1
	v_pk_add_f32 v[32:33], v[32:33], v[34:35]
	s_nop 1
	v_mov_b32_dpp v34, v32 quad_perm:[2,3,0,1] row_mask:0xf bank_mask:0xf bound_ctrl:1
	v_mov_b32_dpp v35, v33 quad_perm:[2,3,0,1] row_mask:0xf bank_mask:0xf bound_ctrl:1
	v_pk_add_f32 v[32:33], v[32:33], v[34:35]
	s_nop 1
	v_mov_b32_dpp v34, v32 row_half_mirror row_mask:0xf bank_mask:0xf bound_ctrl:1
	v_mov_b32_dpp v35, v33 row_half_mirror row_mask:0xf bank_mask:0xf bound_ctrl:1
	s_and_saveexec_b64 s[20:21], s[14:15]
	v_pk_add_f32 v[32:33], v[32:33], v[34:35]
	ds_write_b64 v153, v[32:33] offset:49152
	s_or_b64 exec, exec, s[20:21]
	s_waitcnt lgkmcnt(1)
	v_pk_mul_f32 v[202:203], v[38:39], v[66:67] op_sel_hi:[0,1]
	v_pk_fma_f32 v[202:203], v[36:37], v[2:3], v[202:203] op_sel_hi:[0,1,1]
	v_pk_mul_f32 v[38:39], v[38:39], v[64:65] op_sel:[1,0]
	v_pk_fma_f32 v[36:37], v[36:37], v[68:69], v[38:39] op_sel:[1,0,0]
	s_waitcnt lgkmcnt(0)
	v_pk_fma_f32 v[38:39], v[28:29], v[62:63], v[202:203] op_sel_hi:[0,1,1]
	v_pk_fma_f32 v[28:29], v[28:29], v[60:61], v[36:37] op_sel:[1,0,0]
	v_pk_fma_f32 v[36:37], v[30:31], v[46:47], v[38:39] op_sel_hi:[0,1,1]
	v_pk_fma_f32 v[28:29], v[30:31], v[44:45], v[28:29] op_sel:[1,0,0]
	v_pk_add_f32 v[28:29], v[36:37], v[28:29]
	ds_read_b128 v[70:73], v152 offset:4352
	ds_read_b128 v[154:157], v152 offset:4368
	ds_read_b128 v[158:161], v152 offset:8448
	ds_read_b128 v[166:169], v152 offset:8464
	ds_read_b128 v[170:173], v152 offset:12544
	ds_read_b128 v[174:177], v152 offset:12560
	ds_read_b128 v[178:181], v152 offset:16640
	ds_read_b128 v[198:201], v152 offset:16656
	ds_read_b64 v[74:75], v151 offset:20736
	ds_read_b128 v[40:43], v1 offset:512
	ds_read_b128 v[32:35], v1 offset:528
	v_mov_b32_dpp v30, v28 quad_perm:[1,0,3,2] row_mask:0xf bank_mask:0xf bound_ctrl:1
	v_mov_b32_dpp v31, v29 quad_perm:[1,0,3,2] row_mask:0xf bank_mask:0xf bound_ctrl:1
	v_pk_add_f32 v[28:29], v[28:29], v[30:31]
	s_nop 1
	v_mov_b32_dpp v30, v28 quad_perm:[2,3,0,1] row_mask:0xf bank_mask:0xf bound_ctrl:1
	v_mov_b32_dpp v31, v29 quad_perm:[2,3,0,1] row_mask:0xf bank_mask:0xf bound_ctrl:1
	v_pk_add_f32 v[28:29], v[28:29], v[30:31]
	s_nop 1
	v_mov_b32_dpp v30, v28 row_half_mirror row_mask:0xf bank_mask:0xf bound_ctrl:1
	v_mov_b32_dpp v31, v29 row_half_mirror row_mask:0xf bank_mask:0xf bound_ctrl:1
	v_pk_add_f32 v[28:29], v[28:29], v[30:31]
	s_waitcnt lgkmcnt(8)
	v_pk_mul_f32 v[30:31], v[158:159], v[28:29] op_sel_hi:[0,1]
	s_waitcnt lgkmcnt(2)
	v_pk_fma_f32 v[30:31], v[170:171], v[74:75], v[30:31] op_sel_hi:[0,1,1] neg_lo:[0,0,1] neg_hi:[0,0,1]
	v_pk_fma_f32 v[2:3], v[2:3], v[70:71], v[30:31] op_sel_hi:[1,0,1]
	v_pk_mul_f32 v[30:31], v[158:159], v[28:29] op_sel:[1,0]
	v_pk_mul_f32 v[38:39], v[160:161], v[28:29] op_sel_hi:[0,1]
	v_pk_fma_f32 v[30:31], v[170:171], v[74:75], v[30:31] op_sel:[1,0,0] neg_lo:[0,0,1] neg_hi:[0,0,1]
	v_pk_fma_f32 v[38:39], v[172:173], v[74:75], v[38:39] op_sel_hi:[0,1,1] neg_lo:[0,0,1] neg_hi:[0,0,1]
	v_pk_fma_f32 v[68:69], v[68:69], v[70:71], v[30:31] op_sel:[0,1,0]
	v_pk_fma_f32 v[66:67], v[66:67], v[72:73], v[38:39] op_sel_hi:[1,0,1]
	v_pk_mul_f32 v[70:71], v[160:161], v[28:29] op_sel:[1,0]
	v_pk_fma_f32 v[70:71], v[172:173], v[74:75], v[70:71] op_sel:[1,0,0] neg_lo:[0,0,1] neg_hi:[0,0,1]
	v_pk_fma_f32 v[36:37], v[178:179], v[68:69], 0 op_sel:[1,0,0] op_sel_hi:[1,1,0]
	v_pk_fma_f32 v[64:65], v[64:65], v[72:73], v[70:71] op_sel:[0,1,0]
	v_pk_fma_f32 v[36:37], v[180:181], v[64:65], v[36:37] op_sel:[1,0,0]
	v_pk_mul_f32 v[38:39], v[166:167], v[28:29] op_sel_hi:[0,1]
	v_pk_fma_f32 v[38:39], v[174:175], v[74:75], v[38:39] op_sel_hi:[0,1,1] neg_lo:[0,0,1] neg_hi:[0,0,1]
	v_pk_fma_f32 v[62:63], v[62:63], v[154:155], v[38:39] op_sel_hi:[1,0,1]
	v_pk_mul_f32 v[38:39], v[166:167], v[28:29] op_sel:[1,0]
	v_pk_fma_f32 v[30:31], v[178:179], v[2:3], 0 op_sel_hi:[0,1,0]
	v_pk_fma_f32 v[38:39], v[174:175], v[74:75], v[38:39] op_sel:[1,0,0] neg_lo:[0,0,1] neg_hi:[0,0,1]
	v_pk_fma_f32 v[60:61], v[60:61], v[154:155], v[38:39] op_sel:[0,1,0]
	v_pk_mul_f32 v[38:39], v[168:169], v[28:29] op_sel_hi:[0,1]
	v_pk_fma_f32 v[30:31], v[180:181], v[66:67], v[30:31] op_sel_hi:[0,1,1]
	v_pk_fma_f32 v[38:39], v[176:177], v[74:75], v[38:39] op_sel_hi:[0,1,1] neg_lo:[0,0,1] neg_hi:[0,0,1]
	v_pk_mul_f32 v[28:29], v[168:169], v[28:29] op_sel:[1,0]
	v_pk_fma_f32 v[30:31], v[198:199], v[62:63], v[30:31] op_sel_hi:[0,1,1]
	v_pk_fma_f32 v[46:47], v[46:47], v[156:157], v[38:39] op_sel_hi:[1,0,1]
	v_pk_fma_f32 v[28:29], v[176:177], v[74:75], v[28:29] op_sel:[1,0,0] neg_lo:[0,0,1] neg_hi:[0,0,1]
	v_pk_fma_f32 v[36:37], v[198:199], v[60:61], v[36:37] op_sel:[1,0,0]
	v_pk_fma_f32 v[44:45], v[44:45], v[156:157], v[28:29] op_sel:[0,1,0]
	v_pk_fma_f32 v[28:29], v[200:201], v[46:47], v[30:31] op_sel_hi:[0,1,1]
	v_pk_fma_f32 v[30:31], v[200:201], v[44:45], v[36:37] op_sel:[1,0,0]
	v_pk_add_f32 v[28:29], v[28:29], v[30:31]
	s_nop 1
	v_mov_b32_dpp v30, v28 quad_perm:[1,0,3,2] row_mask:0xf bank_mask:0xf bound_ctrl:1
	v_mov_b32_dpp v31, v29 quad_perm:[1,0,3,2] row_mask:0xf bank_mask:0xf bound_ctrl:1
	v_pk_add_f32 v[28:29], v[28:29], v[30:31]
	s_nop 1
	v_mov_b32_dpp v30, v28 quad_perm:[2,3,0,1] row_mask:0xf bank_mask:0xf bound_ctrl:1
	v_mov_b32_dpp v31, v29 quad_perm:[2,3,0,1] row_mask:0xf bank_mask:0xf bound_ctrl:1
	v_pk_add_f32 v[28:29], v[28:29], v[30:31]
	s_nop 1
	v_mov_b32_dpp v30, v28 row_half_mirror row_mask:0xf bank_mask:0xf bound_ctrl:1
	v_mov_b32_dpp v31, v29 row_half_mirror row_mask:0xf bank_mask:0xf bound_ctrl:1
	s_and_saveexec_b64 s[20:21], s[14:15]
	v_pk_add_f32 v[28:29], v[28:29], v[30:31]
	ds_write_b64 v153, v[28:29] offset:49408
	s_or_b64 exec, exec, s[20:21]
	s_waitcnt lgkmcnt(1)
	v_pk_mul_f32 v[202:203], v[42:43], v[66:67] op_sel_hi:[0,1]
	v_pk_fma_f32 v[202:203], v[40:41], v[2:3], v[202:203] op_sel_hi:[0,1,1]
	v_pk_mul_f32 v[42:43], v[42:43], v[64:65] op_sel:[1,0]
	v_pk_fma_f32 v[40:41], v[40:41], v[68:69], v[42:43] op_sel:[1,0,0]
	s_waitcnt lgkmcnt(0)
	v_pk_fma_f32 v[42:43], v[32:33], v[62:63], v[202:203] op_sel_hi:[0,1,1]
	v_pk_fma_f32 v[32:33], v[32:33], v[60:61], v[40:41] op_sel:[1,0,0]
	v_pk_fma_f32 v[40:41], v[34:35], v[46:47], v[42:43] op_sel_hi:[0,1,1]
	v_pk_fma_f32 v[32:33], v[34:35], v[44:45], v[32:33] op_sel:[1,0,0]
	v_pk_add_f32 v[32:33], v[40:41], v[32:33]
	ds_read_b128 v[70:73], v152 offset:4608
	ds_read_b128 v[154:157], v152 offset:4624
	ds_read_b128 v[158:161], v152 offset:8704
	ds_read_b128 v[166:169], v152 offset:8720
	ds_read_b128 v[170:173], v152 offset:12800
	ds_read_b128 v[174:177], v152 offset:12816
	ds_read_b128 v[178:181], v152 offset:16896
	ds_read_b128 v[198:201], v152 offset:16912
	ds_read_b64 v[74:75], v151 offset:20992
	ds_read_b128 v[36:39], v1 offset:768
	ds_read_b128 v[28:31], v1 offset:784
	v_mov_b32_dpp v34, v32 quad_perm:[1,0,3,2] row_mask:0xf bank_mask:0xf bound_ctrl:1
	v_mov_b32_dpp v35, v33 quad_perm:[1,0,3,2] row_mask:0xf bank_mask:0xf bound_ctrl:1
	v_pk_add_f32 v[32:33], v[32:33], v[34:35]
	s_nop 1
	v_mov_b32_dpp v34, v32 quad_perm:[2,3,0,1] row_mask:0xf bank_mask:0xf bound_ctrl:1
	v_mov_b32_dpp v35, v33 quad_perm:[2,3,0,1] row_mask:0xf bank_mask:0xf bound_ctrl:1
	v_pk_add_f32 v[32:33], v[32:33], v[34:35]
	s_nop 1
	v_mov_b32_dpp v34, v32 row_half_mirror row_mask:0xf bank_mask:0xf bound_ctrl:1
	v_mov_b32_dpp v35, v33 row_half_mirror row_mask:0xf bank_mask:0xf bound_ctrl:1
	v_pk_add_f32 v[32:33], v[32:33], v[34:35]
	s_waitcnt lgkmcnt(8)
	v_pk_mul_f32 v[34:35], v[158:159], v[32:33] op_sel_hi:[0,1]
	s_waitcnt lgkmcnt(2)
	v_pk_fma_f32 v[34:35], v[170:171], v[74:75], v[34:35] op_sel_hi:[0,1,1] neg_lo:[0,0,1] neg_hi:[0,0,1]
	v_pk_fma_f32 v[2:3], v[2:3], v[70:71], v[34:35] op_sel_hi:[1,0,1]
	v_pk_mul_f32 v[34:35], v[158:159], v[32:33] op_sel:[1,0]
	v_pk_mul_f32 v[42:43], v[160:161], v[32:33] op_sel_hi:[0,1]
	v_pk_fma_f32 v[34:35], v[170:171], v[74:75], v[34:35] op_sel:[1,0,0] neg_lo:[0,0,1] neg_hi:[0,0,1]
	v_pk_fma_f32 v[42:43], v[172:173], v[74:75], v[42:43] op_sel_hi:[0,1,1] neg_lo:[0,0,1] neg_hi:[0,0,1]
	v_pk_fma_f32 v[68:69], v[68:69], v[70:71], v[34:35] op_sel:[0,1,0]
	v_pk_fma_f32 v[66:67], v[66:67], v[72:73], v[42:43] op_sel_hi:[1,0,1]
	v_pk_mul_f32 v[70:71], v[160:161], v[32:33] op_sel:[1,0]
	v_pk_fma_f32 v[70:71], v[172:173], v[74:75], v[70:71] op_sel:[1,0,0] neg_lo:[0,0,1] neg_hi:[0,0,1]
	v_pk_fma_f32 v[40:41], v[178:179], v[68:69], 0 op_sel:[1,0,0] op_sel_hi:[1,1,0]
	v_pk_fma_f32 v[64:65], v[64:65], v[72:73], v[70:71] op_sel:[0,1,0]
	v_pk_fma_f32 v[40:41], v[180:181], v[64:65], v[40:41] op_sel:[1,0,0]
	v_pk_mul_f32 v[42:43], v[166:167], v[32:33] op_sel_hi:[0,1]
	v_pk_fma_f32 v[42:43], v[174:175], v[74:75], v[42:43] op_sel_hi:[0,1,1] neg_lo:[0,0,1] neg_hi:[0,0,1]
	v_pk_fma_f32 v[62:63], v[62:63], v[154:155], v[42:43] op_sel_hi:[1,0,1]
	v_pk_mul_f32 v[42:43], v[166:167], v[32:33] op_sel:[1,0]
	v_pk_fma_f32 v[34:35], v[178:179], v[2:3], 0 op_sel_hi:[0,1,0]
	v_pk_fma_f32 v[42:43], v[174:175], v[74:75], v[42:43] op_sel:[1,0,0] neg_lo:[0,0,1] neg_hi:[0,0,1]
	v_pk_fma_f32 v[60:61], v[60:61], v[154:155], v[42:43] op_sel:[0,1,0]
	v_pk_mul_f32 v[42:43], v[168:169], v[32:33] op_sel_hi:[0,1]
	v_pk_fma_f32 v[34:35], v[180:181], v[66:67], v[34:35] op_sel_hi:[0,1,1]
	v_pk_fma_f32 v[42:43], v[176:177], v[74:75], v[42:43] op_sel_hi:[0,1,1] neg_lo:[0,0,1] neg_hi:[0,0,1]
	v_pk_mul_f32 v[32:33], v[168:169], v[32:33] op_sel:[1,0]
	v_pk_fma_f32 v[34:35], v[198:199], v[62:63], v[34:35] op_sel_hi:[0,1,1]
	v_pk_fma_f32 v[46:47], v[46:47], v[156:157], v[42:43] op_sel_hi:[1,0,1]
	v_pk_fma_f32 v[32:33], v[176:177], v[74:75], v[32:33] op_sel:[1,0,0] neg_lo:[0,0,1] neg_hi:[0,0,1]
	v_pk_fma_f32 v[40:41], v[198:199], v[60:61], v[40:41] op_sel:[1,0,0]
	v_pk_fma_f32 v[44:45], v[44:45], v[156:157], v[32:33] op_sel:[0,1,0]
	v_pk_fma_f32 v[32:33], v[200:201], v[46:47], v[34:35] op_sel_hi:[0,1,1]
	v_pk_fma_f32 v[34:35], v[200:201], v[44:45], v[40:41] op_sel:[1,0,0]
	v_pk_add_f32 v[32:33], v[32:33], v[34:35]
	s_nop 1
	v_mov_b32_dpp v34, v32 quad_perm:[1,0,3,2] row_mask:0xf bank_mask:0xf bound_ctrl:1
	v_mov_b32_dpp v35, v33 quad_perm:[1,0,3,2] row_mask:0xf bank_mask:0xf bound_ctrl:1
	v_pk_add_f32 v[32:33], v[32:33], v[34:35]
	s_nop 1
	v_mov_b32_dpp v34, v32 quad_perm:[2,3,0,1] row_mask:0xf bank_mask:0xf bound_ctrl:1
	v_mov_b32_dpp v35, v33 quad_perm:[2,3,0,1] row_mask:0xf bank_mask:0xf bound_ctrl:1
	v_pk_add_f32 v[32:33], v[32:33], v[34:35]
	s_nop 1
	v_mov_b32_dpp v34, v32 row_half_mirror row_mask:0xf bank_mask:0xf bound_ctrl:1
	v_mov_b32_dpp v35, v33 row_half_mirror row_mask:0xf bank_mask:0xf bound_ctrl:1
	s_and_saveexec_b64 s[20:21], s[14:15]
	v_pk_add_f32 v[32:33], v[32:33], v[34:35]
	ds_write_b64 v153, v[32:33] offset:49664
	s_or_b64 exec, exec, s[20:21]
	s_waitcnt lgkmcnt(1)
	v_pk_mul_f32 v[202:203], v[38:39], v[66:67] op_sel_hi:[0,1]
	v_pk_fma_f32 v[202:203], v[36:37], v[2:3], v[202:203] op_sel_hi:[0,1,1]
	v_pk_mul_f32 v[38:39], v[38:39], v[64:65] op_sel:[1,0]
	v_pk_fma_f32 v[36:37], v[36:37], v[68:69], v[38:39] op_sel:[1,0,0]
	s_waitcnt lgkmcnt(0)
	v_pk_fma_f32 v[38:39], v[28:29], v[62:63], v[202:203] op_sel_hi:[0,1,1]
	v_pk_fma_f32 v[28:29], v[28:29], v[60:61], v[36:37] op_sel:[1,0,0]
	v_pk_fma_f32 v[36:37], v[30:31], v[46:47], v[38:39] op_sel_hi:[0,1,1]
	v_pk_fma_f32 v[28:29], v[30:31], v[44:45], v[28:29] op_sel:[1,0,0]
	v_pk_add_f32 v[28:29], v[36:37], v[28:29]
	ds_read_b128 v[70:73], v152 offset:4864
	ds_read_b128 v[154:157], v152 offset:4880
	ds_read_b128 v[158:161], v152 offset:8960
	ds_read_b128 v[166:169], v152 offset:8976
	ds_read_b128 v[170:173], v152 offset:13056
	ds_read_b128 v[174:177], v152 offset:13072
	ds_read_b128 v[178:181], v152 offset:17152
	ds_read_b128 v[198:201], v152 offset:17168
	ds_read_b64 v[74:75], v151 offset:21248
	ds_read_b128 v[40:43], v1 offset:1024
	ds_read_b128 v[32:35], v1 offset:1040
	v_mov_b32_dpp v30, v28 quad_perm:[1,0,3,2] row_mask:0xf bank_mask:0xf bound_ctrl:1
	v_mov_b32_dpp v31, v29 quad_perm:[1,0,3,2] row_mask:0xf bank_mask:0xf bound_ctrl:1
	v_pk_add_f32 v[28:29], v[28:29], v[30:31]
	s_nop 1
	v_mov_b32_dpp v30, v28 quad_perm:[2,3,0,1] row_mask:0xf bank_mask:0xf bound_ctrl:1
	v_mov_b32_dpp v31, v29 quad_perm:[2,3,0,1] row_mask:0xf bank_mask:0xf bound_ctrl:1
	v_pk_add_f32 v[28:29], v[28:29], v[30:31]
	s_nop 1
	v_mov_b32_dpp v30, v28 row_half_mirror row_mask:0xf bank_mask:0xf bound_ctrl:1
	v_mov_b32_dpp v31, v29 row_half_mirror row_mask:0xf bank_mask:0xf bound_ctrl:1
	v_pk_add_f32 v[36:37], v[28:29], v[30:31]
	s_waitcnt lgkmcnt(8)
	v_pk_mul_f32 v[28:29], v[158:159], v[36:37] op_sel_hi:[0,1]
	s_waitcnt lgkmcnt(2)
	v_pk_fma_f32 v[28:29], v[170:171], v[74:75], v[28:29] op_sel_hi:[0,1,1] neg_lo:[0,0,1] neg_hi:[0,0,1]
	v_pk_fma_f32 v[2:3], v[2:3], v[70:71], v[28:29] op_sel_hi:[1,0,1]
	v_pk_mul_f32 v[28:29], v[158:159], v[36:37] op_sel:[1,0]
	v_pk_mul_f32 v[30:31], v[160:161], v[36:37] op_sel_hi:[0,1]
	v_pk_fma_f32 v[28:29], v[170:171], v[74:75], v[28:29] op_sel:[1,0,0] neg_lo:[0,0,1] neg_hi:[0,0,1]
	v_pk_fma_f32 v[30:31], v[172:173], v[74:75], v[30:31] op_sel_hi:[0,1,1] neg_lo:[0,0,1] neg_hi:[0,0,1]
	v_pk_fma_f32 v[28:29], v[68:69], v[70:71], v[28:29] op_sel:[0,1,0]
	v_pk_fma_f32 v[30:31], v[66:67], v[72:73], v[30:31] op_sel_hi:[1,0,1]
	v_pk_mul_f32 v[70:71], v[160:161], v[36:37] op_sel:[1,0]
	v_pk_fma_f32 v[70:71], v[172:173], v[74:75], v[70:71] op_sel:[1,0,0] neg_lo:[0,0,1] neg_hi:[0,0,1]
	v_pk_fma_f32 v[68:69], v[178:179], v[28:29], 0 op_sel:[1,0,0] op_sel_hi:[1,1,0]
	v_pk_fma_f32 v[64:65], v[64:65], v[72:73], v[70:71] op_sel:[0,1,0]
	v_pk_fma_f32 v[66:67], v[180:181], v[64:65], v[68:69] op_sel:[1,0,0]
	v_pk_mul_f32 v[68:69], v[166:167], v[36:37] op_sel_hi:[0,1]
	v_pk_fma_f32 v[68:69], v[174:175], v[74:75], v[68:69] op_sel_hi:[0,1,1] neg_lo:[0,0,1] neg_hi:[0,0,1]
	v_pk_fma_f32 v[62:63], v[62:63], v[154:155], v[68:69] op_sel_hi:[1,0,1]
	v_pk_mul_f32 v[68:69], v[166:167], v[36:37] op_sel:[1,0]
	v_pk_fma_f32 v[38:39], v[178:179], v[2:3], 0 op_sel_hi:[0,1,0]
	v_pk_fma_f32 v[68:69], v[174:175], v[74:75], v[68:69] op_sel:[1,0,0] neg_lo:[0,0,1] neg_hi:[0,0,1]
	v_pk_fma_f32 v[38:39], v[180:181], v[30:31], v[38:39] op_sel_hi:[0,1,1]
	v_pk_fma_f32 v[60:61], v[60:61], v[154:155], v[68:69] op_sel:[0,1,0]
	v_pk_fma_f32 v[70:71], v[198:199], v[60:61], v[66:67] op_sel:[1,0,0]
	v_pk_mul_f32 v[66:67], v[168:169], v[36:37] op_sel_hi:[0,1]
	v_pk_fma_f32 v[66:67], v[176:177], v[74:75], v[66:67] op_sel_hi:[0,1,1] neg_lo:[0,0,1] neg_hi:[0,0,1]
	v_pk_mul_f32 v[36:37], v[168:169], v[36:37] op_sel:[1,0]
	v_pk_fma_f32 v[38:39], v[198:199], v[62:63], v[38:39] op_sel_hi:[0,1,1]
	v_pk_fma_f32 v[66:67], v[46:47], v[156:157], v[66:67] op_sel_hi:[1,0,1]
	v_pk_fma_f32 v[36:37], v[176:177], v[74:75], v[36:37] op_sel:[1,0,0] neg_lo:[0,0,1] neg_hi:[0,0,1]
	v_pk_fma_f32 v[68:69], v[44:45], v[156:157], v[36:37] op_sel:[0,1,0]
	v_pk_fma_f32 v[36:37], v[200:201], v[66:67], v[38:39] op_sel_hi:[0,1,1]
	v_pk_fma_f32 v[38:39], v[200:201], v[68:69], v[70:71] op_sel:[1,0,0]
	v_pk_add_f32 v[36:37], v[36:37], v[38:39]
	s_nop 1
	v_mov_b32_dpp v38, v36 quad_perm:[1,0,3,2] row_mask:0xf bank_mask:0xf bound_ctrl:1
	v_mov_b32_dpp v39, v37 quad_perm:[1,0,3,2] row_mask:0xf bank_mask:0xf bound_ctrl:1
	v_pk_add_f32 v[36:37], v[36:37], v[38:39]
	s_nop 1
	v_mov_b32_dpp v38, v36 quad_perm:[2,3,0,1] row_mask:0xf bank_mask:0xf bound_ctrl:1
	v_mov_b32_dpp v39, v37 quad_perm:[2,3,0,1] row_mask:0xf bank_mask:0xf bound_ctrl:1
	v_pk_add_f32 v[36:37], v[36:37], v[38:39]
	s_nop 1
	v_mov_b32_dpp v38, v36 row_half_mirror row_mask:0xf bank_mask:0xf bound_ctrl:1
	v_mov_b32_dpp v39, v37 row_half_mirror row_mask:0xf bank_mask:0xf bound_ctrl:1
	s_and_saveexec_b64 s[20:21], s[14:15]
	v_pk_add_f32 v[36:37], v[36:37], v[38:39]
	ds_write_b64 v153, v[36:37] offset:49920
	s_or_b64 exec, exec, s[20:21]
	s_waitcnt lgkmcnt(1)
	v_pk_mul_f32 v[202:203], v[42:43], v[30:31] op_sel_hi:[0,1]
	v_pk_fma_f32 v[202:203], v[40:41], v[2:3], v[202:203] op_sel_hi:[0,1,1]
	v_pk_mul_f32 v[42:43], v[42:43], v[64:65] op_sel:[1,0]
	v_pk_fma_f32 v[40:41], v[40:41], v[28:29], v[42:43] op_sel:[1,0,0]
	s_waitcnt lgkmcnt(0)
	v_pk_fma_f32 v[42:43], v[32:33], v[62:63], v[202:203] op_sel_hi:[0,1,1]
	v_pk_fma_f32 v[32:33], v[32:33], v[60:61], v[40:41] op_sel:[1,0,0]
	v_pk_fma_f32 v[40:41], v[34:35], v[66:67], v[42:43] op_sel_hi:[0,1,1]
	v_pk_fma_f32 v[32:33], v[34:35], v[68:69], v[32:33] op_sel:[1,0,0]
	v_pk_add_f32 v[32:33], v[40:41], v[32:33]
	ds_read_b128 v[70:73], v152 offset:5120
	ds_read_b128 v[154:157], v152 offset:5136
	ds_read_b128 v[158:161], v152 offset:9216
	ds_read_b128 v[166:169], v152 offset:9232
	ds_read_b128 v[170:173], v152 offset:13312
	ds_read_b128 v[174:177], v152 offset:13328
	ds_read_b128 v[178:181], v152 offset:17408
	ds_read_b128 v[198:201], v152 offset:17424
	ds_read_b64 v[74:75], v151 offset:21504
	ds_read_b128 v[44:47], v1 offset:1280
	ds_read_b128 v[36:39], v1 offset:1296
	v_mov_b32_dpp v34, v32 quad_perm:[1,0,3,2] row_mask:0xf bank_mask:0xf bound_ctrl:1
	v_mov_b32_dpp v35, v33 quad_perm:[1,0,3,2] row_mask:0xf bank_mask:0xf bound_ctrl:1
	v_pk_add_f32 v[32:33], v[32:33], v[34:35]
	s_nop 1
	v_mov_b32_dpp v34, v32 quad_perm:[2,3,0,1] row_mask:0xf bank_mask:0xf bound_ctrl:1
	v_mov_b32_dpp v35, v33 quad_perm:[2,3,0,1] row_mask:0xf bank_mask:0xf bound_ctrl:1
	v_pk_add_f32 v[32:33], v[32:33], v[34:35]
	s_nop 1
	v_mov_b32_dpp v34, v32 row_half_mirror row_mask:0xf bank_mask:0xf bound_ctrl:1
	v_mov_b32_dpp v35, v33 row_half_mirror row_mask:0xf bank_mask:0xf bound_ctrl:1
	v_pk_add_f32 v[32:33], v[32:33], v[34:35]
	s_waitcnt lgkmcnt(8)
	v_pk_mul_f32 v[34:35], v[158:159], v[32:33] op_sel_hi:[0,1]
	s_waitcnt lgkmcnt(2)
	v_pk_fma_f32 v[34:35], v[170:171], v[74:75], v[34:35] op_sel_hi:[0,1,1] neg_lo:[0,0,1] neg_hi:[0,0,1]
	v_pk_fma_f32 v[2:3], v[2:3], v[70:71], v[34:35] op_sel_hi:[1,0,1]
	v_pk_mul_f32 v[34:35], v[158:159], v[32:33] op_sel:[1,0]
	v_pk_mul_f32 v[42:43], v[160:161], v[32:33] op_sel_hi:[0,1]
	v_pk_fma_f32 v[34:35], v[170:171], v[74:75], v[34:35] op_sel:[1,0,0] neg_lo:[0,0,1] neg_hi:[0,0,1]
	v_pk_fma_f32 v[42:43], v[172:173], v[74:75], v[42:43] op_sel_hi:[0,1,1] neg_lo:[0,0,1] neg_hi:[0,0,1]
	v_pk_fma_f32 v[40:41], v[28:29], v[70:71], v[34:35] op_sel:[0,1,0]
	v_pk_fma_f32 v[42:43], v[30:31], v[72:73], v[42:43] op_sel_hi:[1,0,1]
	v_pk_mul_f32 v[70:71], v[160:161], v[32:33] op_sel:[1,0]
	v_pk_fma_f32 v[70:71], v[172:173], v[74:75], v[70:71] op_sel:[1,0,0] neg_lo:[0,0,1] neg_hi:[0,0,1]
	v_pk_fma_f32 v[34:35], v[178:179], v[40:41], 0 op_sel:[1,0,0] op_sel_hi:[1,1,0]
	v_pk_fma_f32 v[64:65], v[64:65], v[72:73], v[70:71] op_sel:[0,1,0]
	v_pk_fma_f32 v[30:31], v[180:181], v[64:65], v[34:35] op_sel:[1,0,0]
	v_pk_mul_f32 v[34:35], v[166:167], v[32:33] op_sel_hi:[0,1]
	v_pk_fma_f32 v[34:35], v[174:175], v[74:75], v[34:35] op_sel_hi:[0,1,1] neg_lo:[0,0,1] neg_hi:[0,0,1]
	v_pk_fma_f32 v[62:63], v[62:63], v[154:155], v[34:35] op_sel_hi:[1,0,1]
	v_pk_mul_f32 v[34:35], v[166:167], v[32:33] op_sel:[1,0]
	v_pk_fma_f32 v[28:29], v[178:179], v[2:3], 0 op_sel_hi:[0,1,0]
	v_pk_fma_f32 v[34:35], v[174:175], v[74:75], v[34:35] op_sel:[1,0,0] neg_lo:[0,0,1] neg_hi:[0,0,1]
	v_pk_fma_f32 v[60:61], v[60:61], v[154:155], v[34:35] op_sel:[0,1,0]
	v_pk_mul_f32 v[34:35], v[168:169], v[32:33] op_sel_hi:[0,1]
	v_pk_fma_f32 v[34:35], v[176:177], v[74:75], v[34:35] op_sel_hi:[0,1,1] neg_lo:[0,0,1] neg_hi:[0,0,1]
	v_pk_fma_f32 v[72:73], v[66:67], v[156:157], v[34:35] op_sel_hi:[1,0,1]
	v_pk_mul_f32 v[32:33], v[168:169], v[32:33] op_sel:[1,0]
	v_pk_fma_f32 v[28:29], v[180:181], v[42:43], v[28:29] op_sel_hi:[0,1,1]
	v_pk_fma_f32 v[32:33], v[176:177], v[74:75], v[32:33] op_sel:[1,0,0] neg_lo:[0,0,1] neg_hi:[0,0,1]
	v_pk_fma_f32 v[28:29], v[198:199], v[62:63], v[28:29] op_sel_hi:[0,1,1]
	v_pk_fma_f32 v[30:31], v[198:199], v[60:61], v[30:31] op_sel:[1,0,0]
	v_pk_fma_f32 v[74:75], v[68:69], v[156:157], v[32:33] op_sel:[0,1,0]
	v_pk_fma_f32 v[28:29], v[200:201], v[72:73], v[28:29] op_sel_hi:[0,1,1]
	v_pk_fma_f32 v[30:31], v[200:201], v[74:75], v[30:31] op_sel:[1,0,0]
	v_pk_add_f32 v[28:29], v[28:29], v[30:31]
	s_nop 1
	v_mov_b32_dpp v30, v28 quad_perm:[1,0,3,2] row_mask:0xf bank_mask:0xf bound_ctrl:1
	v_mov_b32_dpp v31, v29 quad_perm:[1,0,3,2] row_mask:0xf bank_mask:0xf bound_ctrl:1
	v_pk_add_f32 v[28:29], v[28:29], v[30:31]
	s_nop 1
	v_mov_b32_dpp v30, v28 quad_perm:[2,3,0,1] row_mask:0xf bank_mask:0xf bound_ctrl:1
	v_mov_b32_dpp v31, v29 quad_perm:[2,3,0,1] row_mask:0xf bank_mask:0xf bound_ctrl:1
	v_pk_add_f32 v[28:29], v[28:29], v[30:31]
	s_nop 1
	v_mov_b32_dpp v30, v28 row_half_mirror row_mask:0xf bank_mask:0xf bound_ctrl:1
	v_mov_b32_dpp v31, v29 row_half_mirror row_mask:0xf bank_mask:0xf bound_ctrl:1
	s_and_saveexec_b64 s[20:21], s[14:15]
	v_pk_add_f32 v[28:29], v[28:29], v[30:31]
	ds_write_b64 v153, v[28:29] offset:50176
	s_or_b64 exec, exec, s[20:21]
	s_waitcnt lgkmcnt(1)
	v_pk_mul_f32 v[66:67], v[46:47], v[42:43] op_sel_hi:[0,1]
	v_pk_fma_f32 v[66:67], v[44:45], v[2:3], v[66:67] op_sel_hi:[0,1,1]
	v_pk_mul_f32 v[46:47], v[46:47], v[64:65] op_sel:[1,0]
	v_pk_fma_f32 v[44:45], v[44:45], v[40:41], v[46:47] op_sel:[1,0,0]
	s_waitcnt lgkmcnt(0)
	v_pk_fma_f32 v[46:47], v[36:37], v[62:63], v[66:67] op_sel_hi:[0,1,1]
	v_pk_fma_f32 v[36:37], v[36:37], v[60:61], v[44:45] op_sel:[1,0,0]
	v_pk_fma_f32 v[44:45], v[38:39], v[72:73], v[46:47] op_sel_hi:[0,1,1]
	v_pk_fma_f32 v[36:37], v[38:39], v[74:75], v[36:37] op_sel:[1,0,0]
	v_pk_add_f32 v[36:37], v[44:45], v[36:37]
	ds_read_b128 v[154:157], v152 offset:5376
	ds_read_b128 v[158:161], v152 offset:5392
	ds_read_b128 v[166:169], v152 offset:9472
	ds_read_b128 v[170:173], v152 offset:9488
	ds_read_b128 v[174:177], v152 offset:13568
	ds_read_b128 v[178:181], v152 offset:13584
	ds_read_b128 v[198:201], v152 offset:17664
	ds_read_b128 v[202:205], v152 offset:17680
	ds_read_b64 v[206:207], v151 offset:21760
	ds_read_b128 v[32:35], v1 offset:1536
	ds_read_b128 v[28:31], v1 offset:1552
	v_mov_b32_dpp v38, v36 quad_perm:[1,0,3,2] row_mask:0xf bank_mask:0xf bound_ctrl:1
	v_mov_b32_dpp v39, v37 quad_perm:[1,0,3,2] row_mask:0xf bank_mask:0xf bound_ctrl:1
	v_pk_add_f32 v[36:37], v[36:37], v[38:39]
	s_waitcnt lgkmcnt(6)
	v_mov_b32_dpp v38, v36 quad_perm:[2,3,0,1] row_mask:0xf bank_mask:0xf bound_ctrl:1
	v_mov_b32_dpp v39, v37 quad_perm:[2,3,0,1] row_mask:0xf bank_mask:0xf bound_ctrl:1
	v_pk_add_f32 v[36:37], v[36:37], v[38:39]
	s_nop 1
	v_mov_b32_dpp v38, v36 row_half_mirror row_mask:0xf bank_mask:0xf bound_ctrl:1
	v_mov_b32_dpp v39, v37 row_half_mirror row_mask:0xf bank_mask:0xf bound_ctrl:1
	v_pk_add_f32 v[36:37], v[36:37], v[38:39]
	s_nop 0
	v_pk_mul_f32 v[38:39], v[166:167], v[36:37] op_sel_hi:[0,1]
	s_waitcnt lgkmcnt(2)
	v_pk_fma_f32 v[38:39], v[174:175], v[206:207], v[38:39] op_sel_hi:[0,1,1] neg_lo:[0,0,1] neg_hi:[0,0,1]
	v_pk_fma_f32 v[70:71], v[2:3], v[154:155], v[38:39] op_sel_hi:[1,0,1]
	v_pk_mul_f32 v[2:3], v[166:167], v[36:37] op_sel:[1,0]
	s_nop 0
	v_pk_fma_f32 v[2:3], v[174:175], v[206:207], v[2:3] op_sel:[1,0,0] neg_lo:[0,0,1] neg_hi:[0,0,1]
	s_nop 0
	v_pk_fma_f32 v[68:69], v[40:41], v[154:155], v[2:3] op_sel:[0,1,0]
	v_pk_mul_f32 v[40:41], v[168:169], v[36:37] op_sel_hi:[0,1]
	v_pk_fma_f32 v[40:41], v[176:177], v[206:207], v[40:41] op_sel_hi:[0,1,1] neg_lo:[0,0,1] neg_hi:[0,0,1]
	v_pk_fma_f32 v[66:67], v[42:43], v[156:157], v[40:41] op_sel_hi:[1,0,1]
	v_pk_mul_f32 v[42:43], v[168:169], v[36:37] op_sel:[1,0]
	v_pk_fma_f32 v[42:43], v[176:177], v[206:207], v[42:43] op_sel:[1,0,0] neg_lo:[0,0,1] neg_hi:[0,0,1]
	v_pk_fma_f32 v[38:39], v[198:199], v[68:69], 0 op_sel:[1,0,0] op_sel_hi:[1,1,0]
	v_pk_fma_f32 v[64:65], v[64:65], v[156:157], v[42:43] op_sel:[0,1,0]
	v_pk_fma_f32 v[38:39], v[200:201], v[64:65], v[38:39] op_sel:[1,0,0]
	v_pk_mul_f32 v[40:41], v[170:171], v[36:37] op_sel_hi:[0,1]
	v_pk_fma_f32 v[40:41], v[178:179], v[206:207], v[40:41] op_sel_hi:[0,1,1] neg_lo:[0,0,1] neg_hi:[0,0,1]
	v_pk_fma_f32 v[62:63], v[62:63], v[158:159], v[40:41] op_sel_hi:[1,0,1]
	v_pk_mul_f32 v[40:41], v[170:171], v[36:37] op_sel:[1,0]
	v_mov_b32_e32 v42, v173
	v_pk_fma_f32 v[40:41], v[178:179], v[206:207], v[40:41] op_sel:[1,0,0] neg_lo:[0,0,1] neg_hi:[0,0,1]
	v_pk_fma_f32 v[2:3], v[198:199], v[70:71], 0 op_sel_hi:[0,1,0]
	v_pk_fma_f32 v[60:61], v[60:61], v[158:159], v[40:41] op_sel:[0,1,0]
	v_pk_mul_f32 v[40:41], v[172:173], v[36:37] op_sel_hi:[0,1]
	v_pk_fma_f32 v[40:41], v[180:181], v[206:207], v[40:41] op_sel_hi:[0,1,1] neg_lo:[0,0,1] neg_hi:[0,0,1]
	v_pk_mul_f32 v[36:37], v[42:43], v[36:37] op_sel_hi:[0,1]
	v_pk_fma_f32 v[2:3], v[200:201], v[66:67], v[2:3] op_sel_hi:[0,1,1]
	v_pk_fma_f32 v[46:47], v[72:73], v[160:161], v[40:41] op_sel_hi:[1,0,1]
	v_mov_b32_e32 v40, v161
	v_pk_fma_f32 v[36:37], v[180:181], v[206:207], v[36:37] op_sel:[1,0,0] neg_lo:[0,0,1] neg_hi:[0,0,1]
	v_pk_fma_f32 v[2:3], v[202:203], v[62:63], v[2:3] op_sel_hi:[0,1,1]
	v_pk_fma_f32 v[38:39], v[202:203], v[60:61], v[38:39] op_sel:[1,0,0]
	v_pk_fma_f32 v[44:45], v[74:75], v[40:41], v[36:37] op_sel_hi:[1,0,1]
	v_pk_fma_f32 v[2:3], v[204:205], v[46:47], v[2:3] op_sel_hi:[0,1,1]
	v_pk_fma_f32 v[36:37], v[204:205], v[44:45], v[38:39] op_sel:[1,0,0]
	v_pk_add_f32 v[2:3], v[2:3], v[36:37]
	s_nop 1
	v_mov_b32_dpp v36, v2 quad_perm:[1,0,3,2] row_mask:0xf bank_mask:0xf bound_ctrl:1
	v_mov_b32_dpp v37, v3 quad_perm:[1,0,3,2] row_mask:0xf bank_mask:0xf bound_ctrl:1
	v_pk_add_f32 v[2:3], v[2:3], v[36:37]
	s_nop 1
	v_mov_b32_dpp v36, v2 quad_perm:[2,3,0,1] row_mask:0xf bank_mask:0xf bound_ctrl:1
	v_mov_b32_dpp v37, v3 quad_perm:[2,3,0,1] row_mask:0xf bank_mask:0xf bound_ctrl:1
	v_pk_add_f32 v[2:3], v[2:3], v[36:37]
	s_nop 1
	v_mov_b32_dpp v36, v2 row_half_mirror row_mask:0xf bank_mask:0xf bound_ctrl:1
	v_mov_b32_dpp v37, v3 row_half_mirror row_mask:0xf bank_mask:0xf bound_ctrl:1
	s_and_saveexec_b64 s[20:21], s[14:15]
	v_pk_add_f32 v[2:3], v[2:3], v[36:37]
	ds_write_b64 v153, v[2:3] offset:50432
	s_or_b64 exec, exec, s[20:21]
	s_waitcnt lgkmcnt(0)
	v_pk_mul_f32 v[2:3], v[66:67], v[34:35] op_sel_hi:[1,0]
	v_pk_fma_f32 v[2:3], v[70:71], v[32:33], v[2:3] op_sel_hi:[1,0,1]
	v_pk_mul_f32 v[34:35], v[64:65], v[34:35] op_sel:[0,1]
	v_pk_fma_f32 v[2:3], v[62:63], v[28:29], v[2:3] op_sel_hi:[1,0,1]
	v_pk_fma_f32 v[32:33], v[68:69], v[32:33], v[34:35] op_sel:[0,1,0]
	v_pk_fma_f32 v[2:3], v[46:47], v[30:31], v[2:3] op_sel_hi:[1,0,1]
	v_pk_fma_f32 v[28:29], v[60:61], v[28:29], v[32:33] op_sel:[0,1,0]
	v_pk_fma_f32 v[28:29], v[44:45], v[30:31], v[28:29] op_sel:[0,1,0]
	s_nop 0
	v_pk_add_f32 v[2:3], v[2:3], v[28:29]
	s_nop 0
	s_nop 0
	v_mov_b32_dpp v28, v2 quad_perm:[1,0,3,2] row_mask:0xf bank_mask:0xf bound_ctrl:1
	v_mov_b32_dpp v29, v3 quad_perm:[1,0,3,2] row_mask:0xf bank_mask:0xf bound_ctrl:1
	v_pk_add_f32 v[2:3], v[2:3], v[28:29]
	s_nop 0
	s_nop 0
	v_mov_b32_dpp v28, v2 quad_perm:[2,3,0,1] row_mask:0xf bank_mask:0xf bound_ctrl:1
	v_mov_b32_dpp v29, v3 quad_perm:[2,3,0,1] row_mask:0xf bank_mask:0xf bound_ctrl:1
	s_nop 0
	s_nop 0
	v_pk_add_f32 v[2:3], v[2:3], v[28:29]
	s_nop 0
	ds_read_b128 v[72:75], v152 offset:5632
	ds_read_b128 v[154:157], v152 offset:5648
	ds_read_b128 v[158:161], v152 offset:9728
	ds_read_b128 v[166:169], v152 offset:9744
	ds_read_b128 v[170:173], v152 offset:13824
	ds_read_b128 v[174:177], v152 offset:13840
	ds_read_b128 v[178:181], v152 offset:17920
	ds_read_b128 v[198:201], v152 offset:17936
	ds_read_b64 v[202:203], v151 offset:22016
	ds_read_b128 v[40:43], v1 offset:1792
	ds_read_b128 v[36:39], v1 offset:1808
	v_mov_b32_dpp v28, v2 row_half_mirror row_mask:0xf bank_mask:0xf bound_ctrl:1
	v_mov_b32_dpp v29, v3 row_half_mirror row_mask:0xf bank_mask:0xf bound_ctrl:1
	v_pk_add_f32 v[28:29], v[2:3], v[28:29]
	s_nop 0
	s_waitcnt lgkmcnt(8)
	v_pk_mul_f32 v[2:3], v[158:159], v[28:29] op_sel_hi:[0,1]
	s_waitcnt lgkmcnt(2)
	v_pk_fma_f32 v[2:3], v[170:171], v[202:203], v[2:3] op_sel_hi:[0,1,1] neg_lo:[0,0,1] neg_hi:[0,0,1]
	v_pk_mul_f32 v[30:31], v[158:159], v[28:29] op_sel:[1,0]
	v_pk_fma_f32 v[2:3], v[70:71], v[72:73], v[2:3] op_sel_hi:[1,0,1]
	v_pk_fma_f32 v[30:31], v[170:171], v[202:203], v[30:31] op_sel:[1,0,0] neg_lo:[0,0,1] neg_hi:[0,0,1]
	v_pk_mul_f32 v[34:35], v[160:161], v[28:29] op_sel_hi:[0,1]
	v_pk_fma_f32 v[32:33], v[68:69], v[72:73], v[30:31] op_sel:[0,1,0]
	v_pk_fma_f32 v[34:35], v[172:173], v[202:203], v[34:35] op_sel_hi:[0,1,1] neg_lo:[0,0,1] neg_hi:[0,0,1]
	v_pk_mul_f32 v[70:71], v[160:161], v[28:29] op_sel:[1,0]
	v_pk_fma_f32 v[34:35], v[66:67], v[74:75], v[34:35] op_sel_hi:[1,0,1]
	v_pk_fma_f32 v[70:71], v[172:173], v[202:203], v[70:71] op_sel:[1,0,0] neg_lo:[0,0,1] neg_hi:[0,0,1]
	v_pk_fma_f32 v[68:69], v[178:179], v[32:33], 0 op_sel:[1,0,0] op_sel_hi:[1,1,0]
	v_pk_fma_f32 v[64:65], v[64:65], v[74:75], v[70:71] op_sel:[0,1,0]
	v_pk_fma_f32 v[66:67], v[180:181], v[64:65], v[68:69] op_sel:[1,0,0]
	v_pk_mul_f32 v[68:69], v[166:167], v[28:29] op_sel_hi:[0,1]
	v_pk_fma_f32 v[68:69], v[174:175], v[202:203], v[68:69] op_sel_hi:[0,1,1] neg_lo:[0,0,1] neg_hi:[0,0,1]
	v_pk_fma_f32 v[62:63], v[62:63], v[154:155], v[68:69] op_sel_hi:[1,0,1]
	v_pk_mul_f32 v[68:69], v[166:167], v[28:29] op_sel:[1,0]
	v_pk_fma_f32 v[30:31], v[178:179], v[2:3], 0 op_sel_hi:[0,1,0]
	v_pk_fma_f32 v[68:69], v[174:175], v[202:203], v[68:69] op_sel:[1,0,0] neg_lo:[0,0,1] neg_hi:[0,0,1]
	v_pk_fma_f32 v[30:31], v[180:181], v[34:35], v[30:31] op_sel_hi:[0,1,1]
	v_pk_fma_f32 v[60:61], v[60:61], v[154:155], v[68:69] op_sel:[0,1,0]
	v_pk_fma_f32 v[70:71], v[198:199], v[60:61], v[66:67] op_sel:[1,0,0]
	v_pk_mul_f32 v[66:67], v[168:169], v[28:29] op_sel_hi:[0,1]
	v_pk_fma_f32 v[66:67], v[176:177], v[202:203], v[66:67] op_sel_hi:[0,1,1] neg_lo:[0,0,1] neg_hi:[0,0,1]
	v_pk_mul_f32 v[28:29], v[168:169], v[28:29] op_sel:[1,0]
	v_pk_fma_f32 v[30:31], v[198:199], v[62:63], v[30:31] op_sel_hi:[0,1,1]
	v_pk_fma_f32 v[66:67], v[46:47], v[156:157], v[66:67] op_sel_hi:[1,0,1]
	v_pk_fma_f32 v[28:29], v[176:177], v[202:203], v[28:29] op_sel:[1,0,0] neg_lo:[0,0,1] neg_hi:[0,0,1]
	v_pk_fma_f32 v[68:69], v[44:45], v[156:157], v[28:29] op_sel:[0,1,0]
	v_pk_fma_f32 v[28:29], v[200:201], v[66:67], v[30:31] op_sel_hi:[0,1,1]
	v_pk_fma_f32 v[30:31], v[200:201], v[68:69], v[70:71] op_sel:[1,0,0]
	v_pk_add_f32 v[28:29], v[28:29], v[30:31]
	s_nop 0
	s_nop 0
	v_mov_b32_dpp v30, v28 quad_perm:[1,0,3,2] row_mask:0xf bank_mask:0xf bound_ctrl:1
	v_mov_b32_dpp v31, v29 quad_perm:[1,0,3,2] row_mask:0xf bank_mask:0xf bound_ctrl:1
	v_pk_add_f32 v[28:29], v[28:29], v[30:31]
	s_nop 1
	v_mov_b32_dpp v30, v28 quad_perm:[2,3,0,1] row_mask:0xf bank_mask:0xf bound_ctrl:1
	v_mov_b32_dpp v31, v29 quad_perm:[2,3,0,1] row_mask:0xf bank_mask:0xf bound_ctrl:1
	v_pk_add_f32 v[28:29], v[28:29], v[30:31]
	s_nop 1
	v_mov_b32_dpp v30, v28 row_half_mirror row_mask:0xf bank_mask:0xf bound_ctrl:1
	v_mov_b32_dpp v31, v29 row_half_mirror row_mask:0xf bank_mask:0xf bound_ctrl:1
	s_and_saveexec_b64 s[20:21], s[14:15]
	v_pk_add_f32 v[28:29], v[28:29], v[30:31]
	ds_write_b64 v153, v[28:29] offset:50688
	s_or_b64 exec, exec, s[20:21]

.LBB0_612:
	s_andn2_saveexec_b64 s[0:1], s[0:1]
	s_cbranch_execz .LBB0_624
	s_and_b32 s20, s25, 1
	s_mul_i32 s21, s20, 0x6000
	s_add_i32 s21, s21, 0
	s_bitcmp1_b32 s25, 0
	v_lshl_add_u32 v152, v97, 2, s21
	v_lshl_add_u32 v1, v98, 2, s21
	s_cselect_b32 s21, 0x6000, 0
	v_add_u32_e32 v151, s21, v143
	s_lshl_b32 s20, s20, 12
	v_add_u32_e32 v153, s20, v99
	s_waitcnt lgkmcnt(1)
	v_pk_mul_f32 v[202:203], v[42:43], v[34:35] op_sel_hi:[0,1]
	v_pk_fma_f32 v[202:203], v[40:41], v[2:3], v[202:203] op_sel_hi:[0,1,1]
	v_pk_mul_f32 v[42:43], v[42:43], v[64:65] op_sel:[1,0]
	v_pk_fma_f32 v[40:41], v[40:41], v[32:33], v[42:43] op_sel:[1,0,0]
	s_waitcnt lgkmcnt(0)
	v_pk_fma_f32 v[42:43], v[36:37], v[62:63], v[202:203] op_sel_hi:[0,1,1]
	v_pk_fma_f32 v[36:37], v[36:37], v[60:61], v[40:41] op_sel:[1,0,0]
	v_pk_fma_f32 v[40:41], v[38:39], v[66:67], v[42:43] op_sel_hi:[0,1,1]
	v_pk_fma_f32 v[36:37], v[38:39], v[68:69], v[36:37] op_sel:[1,0,0]
	v_pk_add_f32 v[36:37], v[40:41], v[36:37]
	ds_read_b128 v[70:73], v152 offset:5888
	ds_read_b128 v[154:157], v152 offset:5904
	ds_read_b128 v[158:161], v152 offset:9984
	ds_read_b128 v[166:169], v152 offset:10000
	ds_read_b128 v[170:173], v152 offset:14080
	ds_read_b128 v[174:177], v152 offset:14096
	ds_read_b128 v[178:181], v152 offset:18176
	ds_read_b128 v[198:201], v152 offset:18192
	ds_read_b64 v[74:75], v1 offset:22272
	ds_read_b128 v[44:47], v151 offset:2048
	ds_read_b128 v[28:31], v151 offset:2064
	v_mov_b32_dpp v38, v36 quad_perm:[1,0,3,2] row_mask:0xf bank_mask:0xf bound_ctrl:1
	v_mov_b32_dpp v39, v37 quad_perm:[1,0,3,2] row_mask:0xf bank_mask:0xf bound_ctrl:1
	v_pk_add_f32 v[36:37], v[36:37], v[38:39]
	s_nop 1
	v_mov_b32_dpp v38, v36 quad_perm:[2,3,0,1] row_mask:0xf bank_mask:0xf bound_ctrl:1
	v_mov_b32_dpp v39, v37 quad_perm:[2,3,0,1] row_mask:0xf bank_mask:0xf bound_ctrl:1
	v_pk_add_f32 v[36:37], v[36:37], v[38:39]
	s_nop 1
	v_mov_b32_dpp v38, v36 row_half_mirror row_mask:0xf bank_mask:0xf bound_ctrl:1
	v_mov_b32_dpp v39, v37 row_half_mirror row_mask:0xf bank_mask:0xf bound_ctrl:1
	v_pk_add_f32 v[40:41], v[36:37], v[38:39]
	s_waitcnt lgkmcnt(8)
	v_pk_mul_f32 v[36:37], v[158:159], v[40:41] op_sel_hi:[0,1]
	s_waitcnt lgkmcnt(2)
	v_pk_fma_f32 v[36:37], v[170:171], v[74:75], v[36:37] op_sel_hi:[0,1,1] neg_lo:[0,0,1] neg_hi:[0,0,1]
	v_pk_fma_f32 v[2:3], v[2:3], v[70:71], v[36:37] op_sel_hi:[1,0,1]
	v_pk_mul_f32 v[36:37], v[158:159], v[40:41] op_sel:[1,0]
	v_pk_mul_f32 v[38:39], v[160:161], v[40:41] op_sel_hi:[0,1]
	v_pk_fma_f32 v[36:37], v[170:171], v[74:75], v[36:37] op_sel:[1,0,0] neg_lo:[0,0,1] neg_hi:[0,0,1]
	v_pk_fma_f32 v[38:39], v[172:173], v[74:75], v[38:39] op_sel_hi:[0,1,1] neg_lo:[0,0,1] neg_hi:[0,0,1]
	v_pk_fma_f32 v[36:37], v[32:33], v[70:71], v[36:37] op_sel:[0,1,0]
	v_pk_fma_f32 v[38:39], v[34:35], v[72:73], v[38:39] op_sel_hi:[1,0,1]
	v_pk_mul_f32 v[70:71], v[160:161], v[40:41] op_sel:[1,0]
	v_pk_fma_f32 v[70:71], v[172:173], v[74:75], v[70:71] op_sel:[1,0,0] neg_lo:[0,0,1] neg_hi:[0,0,1]
	v_pk_fma_f32 v[42:43], v[178:179], v[36:37], 0 op_sel:[1,0,0] op_sel_hi:[1,1,0]
	v_pk_fma_f32 v[64:65], v[64:65], v[72:73], v[70:71] op_sel:[0,1,0]
	v_pk_fma_f32 v[34:35], v[180:181], v[64:65], v[42:43] op_sel:[1,0,0]
	v_pk_mul_f32 v[42:43], v[166:167], v[40:41] op_sel_hi:[0,1]
	v_pk_fma_f32 v[42:43], v[174:175], v[74:75], v[42:43] op_sel_hi:[0,1,1] neg_lo:[0,0,1] neg_hi:[0,0,1]
	v_pk_fma_f32 v[62:63], v[62:63], v[154:155], v[42:43] op_sel_hi:[1,0,1]
	v_pk_mul_f32 v[42:43], v[166:167], v[40:41] op_sel:[1,0]
	v_pk_fma_f32 v[42:43], v[174:175], v[74:75], v[42:43] op_sel:[1,0,0] neg_lo:[0,0,1] neg_hi:[0,0,1]
	v_pk_fma_f32 v[32:33], v[178:179], v[2:3], 0 op_sel_hi:[0,1,0]
	v_pk_fma_f32 v[60:61], v[60:61], v[154:155], v[42:43] op_sel:[0,1,0]
	v_pk_mul_f32 v[42:43], v[168:169], v[40:41] op_sel_hi:[0,1]
	v_pk_fma_f32 v[42:43], v[176:177], v[74:75], v[42:43] op_sel_hi:[0,1,1] neg_lo:[0,0,1] neg_hi:[0,0,1]
	v_pk_mul_f32 v[40:41], v[168:169], v[40:41] op_sel:[1,0]
	v_pk_fma_f32 v[32:33], v[180:181], v[38:39], v[32:33] op_sel_hi:[0,1,1]
	v_pk_fma_f32 v[66:67], v[66:67], v[156:157], v[42:43] op_sel_hi:[1,0,1]
	v_pk_fma_f32 v[40:41], v[176:177], v[74:75], v[40:41] op_sel:[1,0,0] neg_lo:[0,0,1] neg_hi:[0,0,1]
	v_pk_fma_f32 v[32:33], v[198:199], v[62:63], v[32:33] op_sel_hi:[0,1,1]
	v_pk_fma_f32 v[34:35], v[198:199], v[60:61], v[34:35] op_sel:[1,0,0]
	v_pk_fma_f32 v[68:69], v[68:69], v[156:157], v[40:41] op_sel:[0,1,0]
	v_pk_fma_f32 v[32:33], v[200:201], v[66:67], v[32:33] op_sel_hi:[0,1,1]
	v_pk_fma_f32 v[34:35], v[200:201], v[68:69], v[34:35] op_sel:[1,0,0]
	v_pk_add_f32 v[32:33], v[32:33], v[34:35]
	s_nop 1
	v_mov_b32_dpp v34, v32 quad_perm:[1,0,3,2] row_mask:0xf bank_mask:0xf bound_ctrl:1
	v_mov_b32_dpp v35, v33 quad_perm:[1,0,3,2] row_mask:0xf bank_mask:0xf bound_ctrl:1
	v_pk_add_f32 v[32:33], v[32:33], v[34:35]
	s_nop 1
	v_mov_b32_dpp v34, v32 quad_perm:[2,3,0,1] row_mask:0xf bank_mask:0xf bound_ctrl:1
	v_mov_b32_dpp v35, v33 quad_perm:[2,3,0,1] row_mask:0xf bank_mask:0xf bound_ctrl:1
	v_pk_add_f32 v[32:33], v[32:33], v[34:35]
	s_nop 1
	v_mov_b32_dpp v34, v32 row_half_mirror row_mask:0xf bank_mask:0xf bound_ctrl:1
	v_mov_b32_dpp v35, v33 row_half_mirror row_mask:0xf bank_mask:0xf bound_ctrl:1
	s_and_saveexec_b64 s[20:21], s[14:15]
	v_pk_add_f32 v[32:33], v[32:33], v[34:35]
	ds_write_b64 v153, v[32:33] offset:50944
	s_or_b64 exec, exec, s[20:21]
	s_waitcnt lgkmcnt(1)
	v_pk_mul_f32 v[202:203], v[46:47], v[38:39] op_sel_hi:[0,1]
	v_pk_fma_f32 v[202:203], v[44:45], v[2:3], v[202:203] op_sel_hi:[0,1,1]
	v_pk_mul_f32 v[46:47], v[46:47], v[64:65] op_sel:[1,0]
	v_pk_fma_f32 v[44:45], v[44:45], v[36:37], v[46:47] op_sel:[1,0,0]
	s_waitcnt lgkmcnt(0)
	v_pk_fma_f32 v[46:47], v[28:29], v[62:63], v[202:203] op_sel_hi:[0,1,1]
	v_pk_fma_f32 v[28:29], v[28:29], v[60:61], v[44:45] op_sel:[1,0,0]
	v_pk_fma_f32 v[44:45], v[30:31], v[66:67], v[46:47] op_sel_hi:[0,1,1]
	v_pk_fma_f32 v[28:29], v[30:31], v[68:69], v[28:29] op_sel:[1,0,0]
	v_pk_add_f32 v[28:29], v[44:45], v[28:29]
	ds_read_b128 v[70:73], v152 offset:6144
	ds_read_b128 v[154:157], v152 offset:6160
	ds_read_b128 v[158:161], v152 offset:10240
	ds_read_b128 v[166:169], v152 offset:10256
	ds_read_b128 v[170:173], v152 offset:14336
	ds_read_b128 v[174:177], v152 offset:14352
	ds_read_b128 v[178:181], v152 offset:18432
	ds_read_b128 v[198:201], v152 offset:18448
	ds_read_b64 v[74:75], v1 offset:22528
	ds_read_b128 v[40:43], v151 offset:2304
	ds_read_b128 v[32:35], v151 offset:2320
	v_mov_b32_dpp v30, v28 quad_perm:[1,0,3,2] row_mask:0xf bank_mask:0xf bound_ctrl:1
	v_mov_b32_dpp v31, v29 quad_perm:[1,0,3,2] row_mask:0xf bank_mask:0xf bound_ctrl:1
	v_pk_add_f32 v[28:29], v[28:29], v[30:31]
	s_nop 1
	v_mov_b32_dpp v30, v28 quad_perm:[2,3,0,1] row_mask:0xf bank_mask:0xf bound_ctrl:1
	v_mov_b32_dpp v31, v29 quad_perm:[2,3,0,1] row_mask:0xf bank_mask:0xf bound_ctrl:1
	v_pk_add_f32 v[28:29], v[28:29], v[30:31]
	s_nop 1
	v_mov_b32_dpp v30, v28 row_half_mirror row_mask:0xf bank_mask:0xf bound_ctrl:1
	v_mov_b32_dpp v31, v29 row_half_mirror row_mask:0xf bank_mask:0xf bound_ctrl:1
	v_pk_add_f32 v[44:45], v[28:29], v[30:31]
	s_waitcnt lgkmcnt(8)
	v_pk_mul_f32 v[28:29], v[158:159], v[44:45] op_sel_hi:[0,1]
	s_waitcnt lgkmcnt(2)
	v_pk_fma_f32 v[28:29], v[170:171], v[74:75], v[28:29] op_sel_hi:[0,1,1] neg_lo:[0,0,1] neg_hi:[0,0,1]
	v_pk_fma_f32 v[2:3], v[2:3], v[70:71], v[28:29] op_sel_hi:[1,0,1]
	v_pk_mul_f32 v[28:29], v[158:159], v[44:45] op_sel:[1,0]
	v_pk_mul_f32 v[30:31], v[160:161], v[44:45] op_sel_hi:[0,1]
	v_pk_fma_f32 v[28:29], v[170:171], v[74:75], v[28:29] op_sel:[1,0,0] neg_lo:[0,0,1] neg_hi:[0,0,1]
	v_pk_fma_f32 v[30:31], v[172:173], v[74:75], v[30:31] op_sel_hi:[0,1,1] neg_lo:[0,0,1] neg_hi:[0,0,1]
	v_pk_fma_f32 v[28:29], v[36:37], v[70:71], v[28:29] op_sel:[0,1,0]
	v_pk_fma_f32 v[30:31], v[38:39], v[72:73], v[30:31] op_sel_hi:[1,0,1]
	v_pk_mul_f32 v[70:71], v[160:161], v[44:45] op_sel:[1,0]
	v_pk_fma_f32 v[70:71], v[172:173], v[74:75], v[70:71] op_sel:[1,0,0] neg_lo:[0,0,1] neg_hi:[0,0,1]
	v_pk_fma_f32 v[46:47], v[178:179], v[28:29], 0 op_sel:[1,0,0] op_sel_hi:[1,1,0]
	v_pk_fma_f32 v[64:65], v[64:65], v[72:73], v[70:71] op_sel:[0,1,0]
	v_pk_fma_f32 v[38:39], v[180:181], v[64:65], v[46:47] op_sel:[1,0,0]
	v_pk_mul_f32 v[46:47], v[166:167], v[44:45] op_sel_hi:[0,1]
	v_pk_fma_f32 v[46:47], v[174:175], v[74:75], v[46:47] op_sel_hi:[0,1,1] neg_lo:[0,0,1] neg_hi:[0,0,1]
	v_pk_fma_f32 v[62:63], v[62:63], v[154:155], v[46:47] op_sel_hi:[1,0,1]
	v_pk_mul_f32 v[46:47], v[166:167], v[44:45] op_sel:[1,0]
	v_pk_fma_f32 v[46:47], v[174:175], v[74:75], v[46:47] op_sel:[1,0,0] neg_lo:[0,0,1] neg_hi:[0,0,1]
	v_pk_fma_f32 v[36:37], v[178:179], v[2:3], 0 op_sel_hi:[0,1,0]
	v_pk_fma_f32 v[60:61], v[60:61], v[154:155], v[46:47] op_sel:[0,1,0]
	v_pk_mul_f32 v[46:47], v[168:169], v[44:45] op_sel_hi:[0,1]
	v_pk_fma_f32 v[46:47], v[176:177], v[74:75], v[46:47] op_sel_hi:[0,1,1] neg_lo:[0,0,1] neg_hi:[0,0,1]
	v_pk_mul_f32 v[44:45], v[168:169], v[44:45] op_sel:[1,0]
	v_pk_fma_f32 v[36:37], v[180:181], v[30:31], v[36:37] op_sel_hi:[0,1,1]
	v_pk_fma_f32 v[66:67], v[66:67], v[156:157], v[46:47] op_sel_hi:[1,0,1]
	v_pk_fma_f32 v[44:45], v[176:177], v[74:75], v[44:45] op_sel:[1,0,0] neg_lo:[0,0,1] neg_hi:[0,0,1]
	v_pk_fma_f32 v[36:37], v[198:199], v[62:63], v[36:37] op_sel_hi:[0,1,1]
	v_pk_fma_f32 v[38:39], v[198:199], v[60:61], v[38:39] op_sel:[1,0,0]
	v_pk_fma_f32 v[68:69], v[68:69], v[156:157], v[44:45] op_sel:[0,1,0]
	v_pk_fma_f32 v[36:37], v[200:201], v[66:67], v[36:37] op_sel_hi:[0,1,1]
	v_pk_fma_f32 v[38:39], v[200:201], v[68:69], v[38:39] op_sel:[1,0,0]
	v_pk_add_f32 v[36:37], v[36:37], v[38:39]
	s_nop 1
	v_mov_b32_dpp v38, v36 quad_perm:[1,0,3,2] row_mask:0xf bank_mask:0xf bound_ctrl:1
	v_mov_b32_dpp v39, v37 quad_perm:[1,0,3,2] row_mask:0xf bank_mask:0xf bound_ctrl:1
	v_pk_add_f32 v[36:37], v[36:37], v[38:39]
	s_nop 1
	v_mov_b32_dpp v38, v36 quad_perm:[2,3,0,1] row_mask:0xf bank_mask:0xf bound_ctrl:1
	v_mov_b32_dpp v39, v37 quad_perm:[2,3,0,1] row_mask:0xf bank_mask:0xf bound_ctrl:1
	v_pk_add_f32 v[36:37], v[36:37], v[38:39]
	s_nop 1
	v_mov_b32_dpp v38, v36 row_half_mirror row_mask:0xf bank_mask:0xf bound_ctrl:1
	v_mov_b32_dpp v39, v37 row_half_mirror row_mask:0xf bank_mask:0xf bound_ctrl:1
	s_and_saveexec_b64 s[20:21], s[14:15]
	v_pk_add_f32 v[36:37], v[36:37], v[38:39]
	ds_write_b64 v153, v[36:37] offset:51200
	s_or_b64 exec, exec, s[20:21]
	s_waitcnt lgkmcnt(1)
	v_pk_mul_f32 v[202:203], v[42:43], v[30:31] op_sel_hi:[0,1]
	v_pk_fma_f32 v[202:203], v[40:41], v[2:3], v[202:203] op_sel_hi:[0,1,1]
	v_pk_mul_f32 v[42:43], v[42:43], v[64:65] op_sel:[1,0]
	v_pk_fma_f32 v[40:41], v[40:41], v[28:29], v[42:43] op_sel:[1,0,0]
	s_waitcnt lgkmcnt(0)
	v_pk_fma_f32 v[42:43], v[32:33], v[62:63], v[202:203] op_sel_hi:[0,1,1]
	v_pk_fma_f32 v[32:33], v[32:33], v[60:61], v[40:41] op_sel:[1,0,0]
	v_pk_fma_f32 v[40:41], v[34:35], v[66:67], v[42:43] op_sel_hi:[0,1,1]
	v_pk_fma_f32 v[32:33], v[34:35], v[68:69], v[32:33] op_sel:[1,0,0]
	v_pk_add_f32 v[32:33], v[40:41], v[32:33]
	ds_read_b128 v[70:73], v152 offset:6400
	ds_read_b128 v[154:157], v152 offset:6416
	ds_read_b128 v[158:161], v152 offset:10496
	ds_read_b128 v[166:169], v152 offset:10512
	ds_read_b128 v[170:173], v152 offset:14592
	ds_read_b128 v[174:177], v152 offset:14608
	ds_read_b128 v[178:181], v152 offset:18688
	ds_read_b128 v[198:201], v152 offset:18704
	ds_read_b64 v[74:75], v1 offset:22784
	ds_read_b128 v[44:47], v151 offset:2560
	ds_read_b128 v[36:39], v151 offset:2576
	v_mov_b32_dpp v34, v32 quad_perm:[1,0,3,2] row_mask:0xf bank_mask:0xf bound_ctrl:1
	v_mov_b32_dpp v35, v33 quad_perm:[1,0,3,2] row_mask:0xf bank_mask:0xf bound_ctrl:1
	v_pk_add_f32 v[32:33], v[32:33], v[34:35]
	s_nop 1
	v_mov_b32_dpp v34, v32 quad_perm:[2,3,0,1] row_mask:0xf bank_mask:0xf bound_ctrl:1
	v_mov_b32_dpp v35, v33 quad_perm:[2,3,0,1] row_mask:0xf bank_mask:0xf bound_ctrl:1
	v_pk_add_f32 v[32:33], v[32:33], v[34:35]
	s_nop 1
	v_mov_b32_dpp v34, v32 row_half_mirror row_mask:0xf bank_mask:0xf bound_ctrl:1
	v_mov_b32_dpp v35, v33 row_half_mirror row_mask:0xf bank_mask:0xf bound_ctrl:1
	v_pk_add_f32 v[32:33], v[32:33], v[34:35]
	s_waitcnt lgkmcnt(8)
	v_pk_mul_f32 v[34:35], v[158:159], v[32:33] op_sel_hi:[0,1]
	s_waitcnt lgkmcnt(2)
	v_pk_fma_f32 v[34:35], v[170:171], v[74:75], v[34:35] op_sel_hi:[0,1,1] neg_lo:[0,0,1] neg_hi:[0,0,1]
	v_pk_fma_f32 v[2:3], v[2:3], v[70:71], v[34:35] op_sel_hi:[1,0,1]
	v_pk_mul_f32 v[34:35], v[158:159], v[32:33] op_sel:[1,0]
	v_pk_mul_f32 v[42:43], v[160:161], v[32:33] op_sel_hi:[0,1]
	v_pk_fma_f32 v[34:35], v[170:171], v[74:75], v[34:35] op_sel:[1,0,0] neg_lo:[0,0,1] neg_hi:[0,0,1]
	v_pk_fma_f32 v[42:43], v[172:173], v[74:75], v[42:43] op_sel_hi:[0,1,1] neg_lo:[0,0,1] neg_hi:[0,0,1]
	v_pk_fma_f32 v[40:41], v[28:29], v[70:71], v[34:35] op_sel:[0,1,0]
	v_pk_fma_f32 v[42:43], v[30:31], v[72:73], v[42:43] op_sel_hi:[1,0,1]
	v_pk_mul_f32 v[70:71], v[160:161], v[32:33] op_sel:[1,0]
	v_pk_fma_f32 v[70:71], v[172:173], v[74:75], v[70:71] op_sel:[1,0,0] neg_lo:[0,0,1] neg_hi:[0,0,1]
	v_pk_fma_f32 v[34:35], v[178:179], v[40:41], 0 op_sel:[1,0,0] op_sel_hi:[1,1,0]
	v_pk_fma_f32 v[64:65], v[64:65], v[72:73], v[70:71] op_sel:[0,1,0]
	v_pk_fma_f32 v[30:31], v[180:181], v[64:65], v[34:35] op_sel:[1,0,0]
	v_pk_mul_f32 v[34:35], v[166:167], v[32:33] op_sel_hi:[0,1]
	v_pk_fma_f32 v[34:35], v[174:175], v[74:75], v[34:35] op_sel_hi:[0,1,1] neg_lo:[0,0,1] neg_hi:[0,0,1]
	v_pk_fma_f32 v[62:63], v[62:63], v[154:155], v[34:35] op_sel_hi:[1,0,1]
	v_pk_mul_f32 v[34:35], v[166:167], v[32:33] op_sel:[1,0]
	v_pk_fma_f32 v[28:29], v[178:179], v[2:3], 0 op_sel_hi:[0,1,0]
	v_pk_fma_f32 v[34:35], v[174:175], v[74:75], v[34:35] op_sel:[1,0,0] neg_lo:[0,0,1] neg_hi:[0,0,1]
	v_pk_fma_f32 v[60:61], v[60:61], v[154:155], v[34:35] op_sel:[0,1,0]
	v_pk_mul_f32 v[34:35], v[168:169], v[32:33] op_sel_hi:[0,1]
	v_pk_fma_f32 v[34:35], v[176:177], v[74:75], v[34:35] op_sel_hi:[0,1,1] neg_lo:[0,0,1] neg_hi:[0,0,1]
	v_pk_fma_f32 v[72:73], v[66:67], v[156:157], v[34:35] op_sel_hi:[1,0,1]
	v_pk_mul_f32 v[32:33], v[168:169], v[32:33] op_sel:[1,0]
	v_pk_fma_f32 v[28:29], v[180:181], v[42:43], v[28:29] op_sel_hi:[0,1,1]
	v_pk_fma_f32 v[32:33], v[176:177], v[74:75], v[32:33] op_sel:[1,0,0] neg_lo:[0,0,1] neg_hi:[0,0,1]
	v_pk_fma_f32 v[28:29], v[198:199], v[62:63], v[28:29] op_sel_hi:[0,1,1]
	v_pk_fma_f32 v[30:31], v[198:199], v[60:61], v[30:31] op_sel:[1,0,0]
	v_pk_fma_f32 v[74:75], v[68:69], v[156:157], v[32:33] op_sel:[0,1,0]
	v_pk_fma_f32 v[28:29], v[200:201], v[72:73], v[28:29] op_sel_hi:[0,1,1]
	v_pk_fma_f32 v[30:31], v[200:201], v[74:75], v[30:31] op_sel:[1,0,0]
	v_pk_add_f32 v[28:29], v[28:29], v[30:31]
	s_nop 1
	v_mov_b32_dpp v30, v28 quad_perm:[1,0,3,2] row_mask:0xf bank_mask:0xf bound_ctrl:1
	v_mov_b32_dpp v31, v29 quad_perm:[1,0,3,2] row_mask:0xf bank_mask:0xf bound_ctrl:1
	v_pk_add_f32 v[28:29], v[28:29], v[30:31]
	s_nop 1
	v_mov_b32_dpp v30, v28 quad_perm:[2,3,0,1] row_mask:0xf bank_mask:0xf bound_ctrl:1
	v_mov_b32_dpp v31, v29 quad_perm:[2,3,0,1] row_mask:0xf bank_mask:0xf bound_ctrl:1
	v_pk_add_f32 v[28:29], v[28:29], v[30:31]
	s_nop 1
	v_mov_b32_dpp v30, v28 row_half_mirror row_mask:0xf bank_mask:0xf bound_ctrl:1
	v_mov_b32_dpp v31, v29 row_half_mirror row_mask:0xf bank_mask:0xf bound_ctrl:1
	s_and_saveexec_b64 s[20:21], s[14:15]
	v_pk_add_f32 v[28:29], v[28:29], v[30:31]
	ds_write_b64 v153, v[28:29] offset:51456
	s_or_b64 exec, exec, s[20:21]

.LBB0_635:
	s_andn2_saveexec_b64 s[0:1], s[0:1]
	s_cbranch_execz .LBB0_576
	s_waitcnt lgkmcnt(1)
	v_pk_mul_f32 v[66:67], v[46:47], v[42:43] op_sel_hi:[0,1]
	v_pk_fma_f32 v[66:67], v[44:45], v[2:3], v[66:67] op_sel_hi:[0,1,1]
	v_pk_mul_f32 v[46:47], v[46:47], v[64:65] op_sel:[1,0]
	v_pk_fma_f32 v[44:45], v[44:45], v[40:41], v[46:47] op_sel:[1,0,0]
	s_waitcnt lgkmcnt(0)
	v_pk_fma_f32 v[46:47], v[36:37], v[62:63], v[66:67] op_sel_hi:[0,1,1]
	v_pk_fma_f32 v[36:37], v[36:37], v[60:61], v[44:45] op_sel:[1,0,0]
	v_pk_fma_f32 v[44:45], v[38:39], v[72:73], v[46:47] op_sel_hi:[0,1,1]
	v_pk_fma_f32 v[36:37], v[38:39], v[74:75], v[36:37] op_sel:[1,0,0]
	v_pk_add_f32 v[36:37], v[44:45], v[36:37]
	ds_read_b128 v[154:157], v152 offset:6656
	ds_read_b128 v[158:161], v152 offset:6672
	ds_read_b128 v[166:169], v152 offset:10752
	ds_read_b128 v[170:173], v152 offset:10768
	ds_read_b128 v[174:177], v152 offset:14848
	ds_read_b128 v[178:181], v152 offset:14864
	ds_read_b128 v[198:201], v152 offset:18944
	ds_read_b128 v[202:205], v152 offset:18960
	ds_read_b64 v[206:207], v1 offset:23040
	ds_read_b128 v[32:35], v151 offset:2816
	ds_read_b128 v[28:31], v151 offset:2832
	v_mov_b32_dpp v38, v36 quad_perm:[1,0,3,2] row_mask:0xf bank_mask:0xf bound_ctrl:1
	v_mov_b32_dpp v39, v37 quad_perm:[1,0,3,2] row_mask:0xf bank_mask:0xf bound_ctrl:1
	v_pk_add_f32 v[36:37], v[36:37], v[38:39]
	s_waitcnt lgkmcnt(6)
	v_mov_b32_dpp v38, v36 quad_perm:[2,3,0,1] row_mask:0xf bank_mask:0xf bound_ctrl:1
	v_mov_b32_dpp v39, v37 quad_perm:[2,3,0,1] row_mask:0xf bank_mask:0xf bound_ctrl:1
	v_pk_add_f32 v[36:37], v[36:37], v[38:39]
	s_nop 1
	v_mov_b32_dpp v38, v36 row_half_mirror row_mask:0xf bank_mask:0xf bound_ctrl:1
	v_mov_b32_dpp v39, v37 row_half_mirror row_mask:0xf bank_mask:0xf bound_ctrl:1
	v_pk_add_f32 v[36:37], v[36:37], v[38:39]
	s_nop 0
	v_pk_mul_f32 v[38:39], v[166:167], v[36:37] op_sel_hi:[0,1]
	s_waitcnt lgkmcnt(2)
	v_pk_fma_f32 v[38:39], v[174:175], v[206:207], v[38:39] op_sel_hi:[0,1,1] neg_lo:[0,0,1] neg_hi:[0,0,1]
	v_pk_fma_f32 v[70:71], v[2:3], v[154:155], v[38:39] op_sel_hi:[1,0,1]
	v_pk_mul_f32 v[2:3], v[166:167], v[36:37] op_sel:[1,0]
	s_nop 0
	v_pk_fma_f32 v[2:3], v[174:175], v[206:207], v[2:3] op_sel:[1,0,0] neg_lo:[0,0,1] neg_hi:[0,0,1]
	s_nop 0
	v_pk_fma_f32 v[68:69], v[40:41], v[154:155], v[2:3] op_sel:[0,1,0]
	v_pk_mul_f32 v[40:41], v[168:169], v[36:37] op_sel_hi:[0,1]
	v_pk_fma_f32 v[40:41], v[176:177], v[206:207], v[40:41] op_sel_hi:[0,1,1] neg_lo:[0,0,1] neg_hi:[0,0,1]
	v_pk_fma_f32 v[66:67], v[42:43], v[156:157], v[40:41] op_sel_hi:[1,0,1]
	v_pk_mul_f32 v[42:43], v[168:169], v[36:37] op_sel:[1,0]
	v_pk_fma_f32 v[42:43], v[176:177], v[206:207], v[42:43] op_sel:[1,0,0] neg_lo:[0,0,1] neg_hi:[0,0,1]
	v_pk_fma_f32 v[38:39], v[198:199], v[68:69], 0 op_sel:[1,0,0] op_sel_hi:[1,1,0]
	v_pk_fma_f32 v[64:65], v[64:65], v[156:157], v[42:43] op_sel:[0,1,0]
	v_pk_fma_f32 v[38:39], v[200:201], v[64:65], v[38:39] op_sel:[1,0,0]
	v_pk_mul_f32 v[40:41], v[170:171], v[36:37] op_sel_hi:[0,1]
	v_pk_fma_f32 v[40:41], v[178:179], v[206:207], v[40:41] op_sel_hi:[0,1,1] neg_lo:[0,0,1] neg_hi:[0,0,1]
	v_pk_fma_f32 v[62:63], v[62:63], v[158:159], v[40:41] op_sel_hi:[1,0,1]
	v_pk_mul_f32 v[40:41], v[170:171], v[36:37] op_sel:[1,0]
	v_mov_b32_e32 v42, v173
	v_pk_fma_f32 v[40:41], v[178:179], v[206:207], v[40:41] op_sel:[1,0,0] neg_lo:[0,0,1] neg_hi:[0,0,1]
	v_pk_fma_f32 v[2:3], v[198:199], v[70:71], 0 op_sel_hi:[0,1,0]
	v_pk_fma_f32 v[60:61], v[60:61], v[158:159], v[40:41] op_sel:[0,1,0]
	v_pk_mul_f32 v[40:41], v[172:173], v[36:37] op_sel_hi:[0,1]
	v_pk_fma_f32 v[40:41], v[180:181], v[206:207], v[40:41] op_sel_hi:[0,1,1] neg_lo:[0,0,1] neg_hi:[0,0,1]
	v_pk_mul_f32 v[36:37], v[42:43], v[36:37] op_sel_hi:[0,1]
	v_pk_fma_f32 v[2:3], v[200:201], v[66:67], v[2:3] op_sel_hi:[0,1,1]
	v_pk_fma_f32 v[46:47], v[72:73], v[160:161], v[40:41] op_sel_hi:[1,0,1]
	v_mov_b32_e32 v40, v161
	v_pk_fma_f32 v[36:37], v[180:181], v[206:207], v[36:37] op_sel:[1,0,0] neg_lo:[0,0,1] neg_hi:[0,0,1]
	v_pk_fma_f32 v[2:3], v[202:203], v[62:63], v[2:3] op_sel_hi:[0,1,1]
	v_pk_fma_f32 v[38:39], v[202:203], v[60:61], v[38:39] op_sel:[1,0,0]
	v_pk_fma_f32 v[44:45], v[74:75], v[40:41], v[36:37] op_sel_hi:[1,0,1]
	v_pk_fma_f32 v[2:3], v[204:205], v[46:47], v[2:3] op_sel_hi:[0,1,1]
	v_pk_fma_f32 v[36:37], v[204:205], v[44:45], v[38:39] op_sel:[1,0,0]
	v_pk_add_f32 v[2:3], v[2:3], v[36:37]
	s_nop 1
	v_mov_b32_dpp v36, v2 quad_perm:[1,0,3,2] row_mask:0xf bank_mask:0xf bound_ctrl:1
	v_mov_b32_dpp v37, v3 quad_perm:[1,0,3,2] row_mask:0xf bank_mask:0xf bound_ctrl:1
	v_pk_add_f32 v[2:3], v[2:3], v[36:37]
	s_nop 1
	v_mov_b32_dpp v36, v2 quad_perm:[2,3,0,1] row_mask:0xf bank_mask:0xf bound_ctrl:1
	v_mov_b32_dpp v37, v3 quad_perm:[2,3,0,1] row_mask:0xf bank_mask:0xf bound_ctrl:1
	v_pk_add_f32 v[2:3], v[2:3], v[36:37]
	s_nop 1
	v_mov_b32_dpp v36, v2 row_half_mirror row_mask:0xf bank_mask:0xf bound_ctrl:1
	v_mov_b32_dpp v37, v3 row_half_mirror row_mask:0xf bank_mask:0xf bound_ctrl:1
	s_and_saveexec_b64 s[20:21], s[14:15]
	v_pk_add_f32 v[2:3], v[2:3], v[36:37]
	ds_write_b64 v153, v[2:3] offset:51712
	s_or_b64 exec, exec, s[20:21]
	s_waitcnt lgkmcnt(0)
	v_pk_mul_f32 v[2:3], v[66:67], v[34:35] op_sel_hi:[1,0]
	v_pk_fma_f32 v[2:3], v[70:71], v[32:33], v[2:3] op_sel_hi:[1,0,1]
	v_pk_mul_f32 v[34:35], v[64:65], v[34:35] op_sel:[0,1]
	v_pk_fma_f32 v[2:3], v[62:63], v[28:29], v[2:3] op_sel_hi:[1,0,1]
	v_pk_fma_f32 v[32:33], v[68:69], v[32:33], v[34:35] op_sel:[0,1,0]
	v_pk_fma_f32 v[2:3], v[46:47], v[30:31], v[2:3] op_sel_hi:[1,0,1]
	v_pk_fma_f32 v[28:29], v[60:61], v[28:29], v[32:33] op_sel:[0,1,0]
	v_pk_fma_f32 v[28:29], v[44:45], v[30:31], v[28:29] op_sel:[0,1,0]
	s_and_b32 s20, s25, 1
	v_pk_add_f32 v[2:3], v[2:3], v[28:29]
	s_mul_i32 s21, s20, 0x6000
	s_add_i32 s21, s21, 0
	v_mov_b32_dpp v28, v2 quad_perm:[1,0,3,2] row_mask:0xf bank_mask:0xf bound_ctrl:1
	v_mov_b32_dpp v29, v3 quad_perm:[1,0,3,2] row_mask:0xf bank_mask:0xf bound_ctrl:1
	s_lshl_b32 s22, s20, 12
	v_pk_add_f32 v[2:3], v[2:3], v[28:29]
	s_cmp_eq_u32 s20, 1
	v_lshl_add_u32 v1, v97, 2, s21
	v_mov_b32_dpp v28, v2 quad_perm:[2,3,0,1] row_mask:0xf bank_mask:0xf bound_ctrl:1
	v_mov_b32_dpp v29, v3 quad_perm:[2,3,0,1] row_mask:0xf bank_mask:0xf bound_ctrl:1
	s_cselect_b32 s20, 0x6000, 0
	v_pk_add_f32 v[2:3], v[2:3], v[28:29]
	v_lshl_add_u32 v73, v98, 2, s21
	v_add_u32_e32 v74, s20, v143
	ds_read_b128 v[152:155], v1 offset:6912
	ds_read_b128 v[156:159], v1 offset:6928
	ds_read_b128 v[166:169], v1 offset:11008
	ds_read_b128 v[170:173], v1 offset:11024
	ds_read_b128 v[174:177], v1 offset:15104
	ds_read_b128 v[178:181], v1 offset:15120
	ds_read_b128 v[198:201], v1 offset:19200
	ds_read_b128 v[202:205], v1 offset:19216
	ds_read_b64 v[160:161], v73 offset:23296
	ds_read_b128 v[40:43], v74 offset:3072
	ds_read_b128 v[36:39], v74 offset:3088
	v_mov_b32_dpp v28, v2 row_half_mirror row_mask:0xf bank_mask:0xf bound_ctrl:1
	v_mov_b32_dpp v29, v3 row_half_mirror row_mask:0xf bank_mask:0xf bound_ctrl:1
	v_pk_add_f32 v[28:29], v[2:3], v[28:29]
	s_waitcnt lgkmcnt(6)
	v_pk_mul_f32 v[2:3], v[166:167], v[28:29] op_sel_hi:[0,1]
	s_waitcnt lgkmcnt(2)
	v_pk_fma_f32 v[2:3], v[174:175], v[160:161], v[2:3] op_sel_hi:[0,1,1] neg_lo:[0,0,1] neg_hi:[0,0,1]
	v_pk_fma_f32 v[2:3], v[70:71], v[152:153], v[2:3] op_sel_hi:[1,0,1]
	v_pk_mul_f32 v[30:31], v[166:167], v[28:29] op_sel:[1,0]
	v_pk_mul_f32 v[34:35], v[168:169], v[28:29] op_sel_hi:[0,1]
	v_pk_fma_f32 v[30:31], v[174:175], v[160:161], v[30:31] op_sel:[1,0,0] neg_lo:[0,0,1] neg_hi:[0,0,1]
	v_pk_fma_f32 v[34:35], v[176:177], v[160:161], v[34:35] op_sel_hi:[0,1,1] neg_lo:[0,0,1] neg_hi:[0,0,1]
	v_pk_mul_f32 v[70:71], v[168:169], v[28:29] op_sel:[1,0]
	v_pk_fma_f32 v[68:69], v[68:69], v[152:153], v[30:31] op_sel:[0,1,0]
	v_pk_fma_f32 v[66:67], v[66:67], v[154:155], v[34:35] op_sel_hi:[1,0,1]
	v_pk_fma_f32 v[70:71], v[176:177], v[160:161], v[70:71] op_sel:[1,0,0] neg_lo:[0,0,1] neg_hi:[0,0,1]
	v_pk_fma_f32 v[32:33], v[198:199], v[68:69], 0 op_sel:[1,0,0] op_sel_hi:[1,1,0]
	v_pk_fma_f32 v[64:65], v[64:65], v[154:155], v[70:71] op_sel:[0,1,0]
	v_pk_fma_f32 v[32:33], v[200:201], v[64:65], v[32:33] op_sel:[1,0,0]
	v_pk_mul_f32 v[34:35], v[170:171], v[28:29] op_sel_hi:[0,1]
	v_pk_fma_f32 v[34:35], v[178:179], v[160:161], v[34:35] op_sel_hi:[0,1,1] neg_lo:[0,0,1] neg_hi:[0,0,1]
	v_pk_fma_f32 v[62:63], v[62:63], v[156:157], v[34:35] op_sel_hi:[1,0,1]
	v_pk_mul_f32 v[34:35], v[170:171], v[28:29] op_sel:[1,0]
	v_pk_fma_f32 v[30:31], v[198:199], v[2:3], 0 op_sel_hi:[0,1,0]
	v_pk_fma_f32 v[34:35], v[178:179], v[160:161], v[34:35] op_sel:[1,0,0] neg_lo:[0,0,1] neg_hi:[0,0,1]
	v_pk_fma_f32 v[60:61], v[60:61], v[156:157], v[34:35] op_sel:[0,1,0]
	v_pk_mul_f32 v[34:35], v[172:173], v[28:29] op_sel_hi:[0,1]
	v_pk_fma_f32 v[30:31], v[200:201], v[66:67], v[30:31] op_sel_hi:[0,1,1]
	v_pk_fma_f32 v[34:35], v[180:181], v[160:161], v[34:35] op_sel_hi:[0,1,1] neg_lo:[0,0,1] neg_hi:[0,0,1]
	v_pk_mul_f32 v[28:29], v[172:173], v[28:29] op_sel:[1,0]
	v_pk_fma_f32 v[30:31], v[202:203], v[62:63], v[30:31] op_sel_hi:[0,1,1]
	v_pk_fma_f32 v[46:47], v[46:47], v[158:159], v[34:35] op_sel_hi:[1,0,1]
	v_pk_fma_f32 v[28:29], v[180:181], v[160:161], v[28:29] op_sel:[1,0,0] neg_lo:[0,0,1] neg_hi:[0,0,1]
	v_pk_fma_f32 v[32:33], v[202:203], v[60:61], v[32:33] op_sel:[1,0,0]
	v_pk_fma_f32 v[44:45], v[44:45], v[158:159], v[28:29] op_sel:[0,1,0]
	v_pk_fma_f32 v[28:29], v[204:205], v[46:47], v[30:31] op_sel_hi:[0,1,1]
	v_pk_fma_f32 v[30:31], v[204:205], v[44:45], v[32:33] op_sel:[1,0,0]
	v_pk_add_f32 v[28:29], v[28:29], v[30:31]
	v_add_u32_e32 v72, s22, v99
	s_nop 0
	v_mov_b32_dpp v30, v28 quad_perm:[1,0,3,2] row_mask:0xf bank_mask:0xf bound_ctrl:1
	v_mov_b32_dpp v31, v29 quad_perm:[1,0,3,2] row_mask:0xf bank_mask:0xf bound_ctrl:1
	v_pk_add_f32 v[28:29], v[28:29], v[30:31]
	s_nop 1
	v_mov_b32_dpp v30, v28 quad_perm:[2,3,0,1] row_mask:0xf bank_mask:0xf bound_ctrl:1
	v_mov_b32_dpp v31, v29 quad_perm:[2,3,0,1] row_mask:0xf bank_mask:0xf bound_ctrl:1
	v_pk_add_f32 v[28:29], v[28:29], v[30:31]
	s_nop 1
	v_mov_b32_dpp v30, v28 row_half_mirror row_mask:0xf bank_mask:0xf bound_ctrl:1
	v_mov_b32_dpp v31, v29 row_half_mirror row_mask:0xf bank_mask:0xf bound_ctrl:1
	s_and_saveexec_b64 s[20:21], s[14:15]
	v_pk_add_f32 v[28:29], v[28:29], v[30:31]
	ds_write_b64 v72, v[28:29] offset:51968
	s_or_b64 exec, exec, s[20:21]
	s_waitcnt lgkmcnt(1)
	v_pk_mul_f32 v[160:161], v[42:43], v[66:67] op_sel_hi:[0,1]
	v_pk_fma_f32 v[160:161], v[40:41], v[2:3], v[160:161] op_sel_hi:[0,1,1]
	v_pk_mul_f32 v[42:43], v[42:43], v[64:65] op_sel:[1,0]
	v_pk_fma_f32 v[40:41], v[40:41], v[68:69], v[42:43] op_sel:[1,0,0]
	s_waitcnt lgkmcnt(0)
	v_pk_fma_f32 v[42:43], v[36:37], v[62:63], v[160:161] op_sel_hi:[0,1,1]
	v_pk_fma_f32 v[36:37], v[36:37], v[60:61], v[40:41] op_sel:[1,0,0]
	v_pk_fma_f32 v[40:41], v[38:39], v[46:47], v[42:43] op_sel_hi:[0,1,1]
	v_pk_fma_f32 v[36:37], v[38:39], v[44:45], v[36:37] op_sel:[1,0,0]
	v_pk_add_f32 v[36:37], v[40:41], v[36:37]
	ds_read_b128 v[152:155], v1 offset:7168
	ds_read_b128 v[156:159], v1 offset:7184
	ds_read_b128 v[166:169], v1 offset:11264
	ds_read_b128 v[170:173], v1 offset:11280
	ds_read_b128 v[174:177], v1 offset:15360
	ds_read_b128 v[178:181], v1 offset:15376
	ds_read_b128 v[198:201], v1 offset:19456
	ds_read_b128 v[202:205], v1 offset:19472
	ds_read_b64 v[70:71], v73 offset:23552
	ds_read_b128 v[32:35], v74 offset:3328
	ds_read_b128 v[28:31], v74 offset:3344
	v_mov_b32_dpp v38, v36 quad_perm:[1,0,3,2] row_mask:0xf bank_mask:0xf bound_ctrl:1
	v_mov_b32_dpp v39, v37 quad_perm:[1,0,3,2] row_mask:0xf bank_mask:0xf bound_ctrl:1
	v_pk_add_f32 v[36:37], v[36:37], v[38:39]
	s_nop 1
	v_mov_b32_dpp v38, v36 quad_perm:[2,3,0,1] row_mask:0xf bank_mask:0xf bound_ctrl:1
	v_mov_b32_dpp v39, v37 quad_perm:[2,3,0,1] row_mask:0xf bank_mask:0xf bound_ctrl:1
	v_pk_add_f32 v[36:37], v[36:37], v[38:39]
	s_nop 1
	v_mov_b32_dpp v38, v36 row_half_mirror row_mask:0xf bank_mask:0xf bound_ctrl:1
	v_mov_b32_dpp v39, v37 row_half_mirror row_mask:0xf bank_mask:0xf bound_ctrl:1
	v_pk_add_f32 v[36:37], v[36:37], v[38:39]
	s_waitcnt lgkmcnt(8)
	v_pk_mul_f32 v[38:39], v[166:167], v[36:37] op_sel_hi:[0,1]
	s_waitcnt lgkmcnt(2)
	v_pk_fma_f32 v[38:39], v[174:175], v[70:71], v[38:39] op_sel_hi:[0,1,1] neg_lo:[0,0,1] neg_hi:[0,0,1]
	v_pk_fma_f32 v[2:3], v[2:3], v[152:153], v[38:39] op_sel_hi:[1,0,1]
	v_pk_mul_f32 v[38:39], v[166:167], v[36:37] op_sel:[1,0]
	v_pk_mul_f32 v[42:43], v[168:169], v[36:37] op_sel_hi:[0,1]
	v_pk_fma_f32 v[38:39], v[174:175], v[70:71], v[38:39] op_sel:[1,0,0] neg_lo:[0,0,1] neg_hi:[0,0,1]
	v_pk_fma_f32 v[42:43], v[176:177], v[70:71], v[42:43] op_sel_hi:[0,1,1] neg_lo:[0,0,1] neg_hi:[0,0,1]
	v_pk_fma_f32 v[68:69], v[68:69], v[152:153], v[38:39] op_sel:[0,1,0]
	v_pk_fma_f32 v[66:67], v[66:67], v[154:155], v[42:43] op_sel_hi:[1,0,1]
	v_pk_mul_f32 v[152:153], v[168:169], v[36:37] op_sel:[1,0]
	v_pk_fma_f32 v[152:153], v[176:177], v[70:71], v[152:153] op_sel:[1,0,0] neg_lo:[0,0,1] neg_hi:[0,0,1]
	v_pk_fma_f32 v[40:41], v[198:199], v[68:69], 0 op_sel:[1,0,0] op_sel_hi:[1,1,0]
	v_pk_fma_f32 v[64:65], v[64:65], v[154:155], v[152:153] op_sel:[0,1,0]
	v_pk_fma_f32 v[40:41], v[200:201], v[64:65], v[40:41] op_sel:[1,0,0]
	v_pk_mul_f32 v[42:43], v[170:171], v[36:37] op_sel_hi:[0,1]
	v_pk_fma_f32 v[42:43], v[178:179], v[70:71], v[42:43] op_sel_hi:[0,1,1] neg_lo:[0,0,1] neg_hi:[0,0,1]
	v_pk_fma_f32 v[62:63], v[62:63], v[156:157], v[42:43] op_sel_hi:[1,0,1]
	v_pk_mul_f32 v[42:43], v[170:171], v[36:37] op_sel:[1,0]
	v_pk_fma_f32 v[38:39], v[198:199], v[2:3], 0 op_sel_hi:[0,1,0]
	v_pk_fma_f32 v[42:43], v[178:179], v[70:71], v[42:43] op_sel:[1,0,0] neg_lo:[0,0,1] neg_hi:[0,0,1]
	v_pk_fma_f32 v[60:61], v[60:61], v[156:157], v[42:43] op_sel:[0,1,0]
	v_pk_mul_f32 v[42:43], v[172:173], v[36:37] op_sel_hi:[0,1]
	v_pk_fma_f32 v[38:39], v[200:201], v[66:67], v[38:39] op_sel_hi:[0,1,1]
	v_pk_fma_f32 v[42:43], v[180:181], v[70:71], v[42:43] op_sel_hi:[0,1,1] neg_lo:[0,0,1] neg_hi:[0,0,1]
	v_pk_mul_f32 v[36:37], v[172:173], v[36:37] op_sel:[1,0]
	v_pk_fma_f32 v[38:39], v[202:203], v[62:63], v[38:39] op_sel_hi:[0,1,1]
	v_pk_fma_f32 v[46:47], v[46:47], v[158:159], v[42:43] op_sel_hi:[1,0,1]
	v_pk_fma_f32 v[36:37], v[180:181], v[70:71], v[36:37] op_sel:[1,0,0] neg_lo:[0,0,1] neg_hi:[0,0,1]
	v_pk_fma_f32 v[40:41], v[202:203], v[60:61], v[40:41] op_sel:[1,0,0]
	v_pk_fma_f32 v[44:45], v[44:45], v[158:159], v[36:37] op_sel:[0,1,0]
	v_pk_fma_f32 v[36:37], v[204:205], v[46:47], v[38:39] op_sel_hi:[0,1,1]
	v_pk_fma_f32 v[38:39], v[204:205], v[44:45], v[40:41] op_sel:[1,0,0]
	v_pk_add_f32 v[36:37], v[36:37], v[38:39]
	s_nop 1
	v_mov_b32_dpp v38, v36 quad_perm:[1,0,3,2] row_mask:0xf bank_mask:0xf bound_ctrl:1
	v_mov_b32_dpp v39, v37 quad_perm:[1,0,3,2] row_mask:0xf bank_mask:0xf bound_ctrl:1
	v_pk_add_f32 v[36:37], v[36:37], v[38:39]
	s_nop 1
	v_mov_b32_dpp v38, v36 quad_perm:[2,3,0,1] row_mask:0xf bank_mask:0xf bound_ctrl:1
	v_mov_b32_dpp v39, v37 quad_perm:[2,3,0,1] row_mask:0xf bank_mask:0xf bound_ctrl:1
	v_pk_add_f32 v[36:37], v[36:37], v[38:39]
	s_nop 1
	v_mov_b32_dpp v38, v36 row_half_mirror row_mask:0xf bank_mask:0xf bound_ctrl:1
	v_mov_b32_dpp v39, v37 row_half_mirror row_mask:0xf bank_mask:0xf bound_ctrl:1
	s_and_saveexec_b64 s[20:21], s[14:15]
	v_pk_add_f32 v[36:37], v[36:37], v[38:39]
	ds_write_b64 v72, v[36:37] offset:52224
	s_or_b64 exec, exec, s[20:21]
	s_waitcnt lgkmcnt(1)
	v_pk_mul_f32 v[160:161], v[34:35], v[66:67] op_sel_hi:[0,1]
	v_pk_fma_f32 v[160:161], v[32:33], v[2:3], v[160:161] op_sel_hi:[0,1,1]
	v_pk_mul_f32 v[34:35], v[34:35], v[64:65] op_sel:[1,0]
	v_pk_fma_f32 v[32:33], v[32:33], v[68:69], v[34:35] op_sel:[1,0,0]
	s_waitcnt lgkmcnt(0)
	v_pk_fma_f32 v[34:35], v[28:29], v[62:63], v[160:161] op_sel_hi:[0,1,1]
	v_pk_fma_f32 v[28:29], v[28:29], v[60:61], v[32:33] op_sel:[1,0,0]
	v_pk_fma_f32 v[32:33], v[30:31], v[46:47], v[34:35] op_sel_hi:[0,1,1]
	v_pk_fma_f32 v[28:29], v[30:31], v[44:45], v[28:29] op_sel:[1,0,0]
	v_pk_add_f32 v[28:29], v[32:33], v[28:29]
	ds_read_b128 v[152:155], v1 offset:7424
	ds_read_b128 v[156:159], v1 offset:7440
	ds_read_b128 v[166:169], v1 offset:11520
	ds_read_b128 v[170:173], v1 offset:11536
	ds_read_b128 v[174:177], v1 offset:15616
	ds_read_b128 v[178:181], v1 offset:15632
	ds_read_b128 v[198:201], v1 offset:19712
	ds_read_b128 v[202:205], v1 offset:19728
	ds_read_b64 v[70:71], v73 offset:23808
	ds_read_b128 v[40:43], v74 offset:3584
	ds_read_b128 v[36:39], v74 offset:3600
	v_mov_b32_dpp v30, v28 quad_perm:[1,0,3,2] row_mask:0xf bank_mask:0xf bound_ctrl:1
	v_mov_b32_dpp v31, v29 quad_perm:[1,0,3,2] row_mask:0xf bank_mask:0xf bound_ctrl:1
	v_pk_add_f32 v[28:29], v[28:29], v[30:31]
	s_nop 1
	v_mov_b32_dpp v30, v28 quad_perm:[2,3,0,1] row_mask:0xf bank_mask:0xf bound_ctrl:1
	v_mov_b32_dpp v31, v29 quad_perm:[2,3,0,1] row_mask:0xf bank_mask:0xf bound_ctrl:1
	v_pk_add_f32 v[28:29], v[28:29], v[30:31]
	s_nop 1
	v_mov_b32_dpp v30, v28 row_half_mirror row_mask:0xf bank_mask:0xf bound_ctrl:1
	v_mov_b32_dpp v31, v29 row_half_mirror row_mask:0xf bank_mask:0xf bound_ctrl:1
	v_pk_add_f32 v[28:29], v[28:29], v[30:31]
	s_waitcnt lgkmcnt(8)
	v_pk_mul_f32 v[30:31], v[166:167], v[28:29] op_sel_hi:[0,1]
	s_waitcnt lgkmcnt(2)
	v_pk_fma_f32 v[30:31], v[174:175], v[70:71], v[30:31] op_sel_hi:[0,1,1] neg_lo:[0,0,1] neg_hi:[0,0,1]
	v_pk_fma_f32 v[2:3], v[2:3], v[152:153], v[30:31] op_sel_hi:[1,0,1]
	v_pk_mul_f32 v[30:31], v[166:167], v[28:29] op_sel:[1,0]
	v_pk_mul_f32 v[34:35], v[168:169], v[28:29] op_sel_hi:[0,1]
	v_pk_fma_f32 v[30:31], v[174:175], v[70:71], v[30:31] op_sel:[1,0,0] neg_lo:[0,0,1] neg_hi:[0,0,1]
	v_pk_fma_f32 v[34:35], v[176:177], v[70:71], v[34:35] op_sel_hi:[0,1,1] neg_lo:[0,0,1] neg_hi:[0,0,1]
	v_pk_fma_f32 v[68:69], v[68:69], v[152:153], v[30:31] op_sel:[0,1,0]
	v_pk_fma_f32 v[66:67], v[66:67], v[154:155], v[34:35] op_sel_hi:[1,0,1]
	v_pk_mul_f32 v[152:153], v[168:169], v[28:29] op_sel:[1,0]
	v_pk_fma_f32 v[152:153], v[176:177], v[70:71], v[152:153] op_sel:[1,0,0] neg_lo:[0,0,1] neg_hi:[0,0,1]
	v_pk_fma_f32 v[32:33], v[198:199], v[68:69], 0 op_sel:[1,0,0] op_sel_hi:[1,1,0]
	v_pk_fma_f32 v[64:65], v[64:65], v[154:155], v[152:153] op_sel:[0,1,0]
	v_pk_fma_f32 v[32:33], v[200:201], v[64:65], v[32:33] op_sel:[1,0,0]
	v_pk_mul_f32 v[34:35], v[170:171], v[28:29] op_sel_hi:[0,1]
	v_pk_fma_f32 v[34:35], v[178:179], v[70:71], v[34:35] op_sel_hi:[0,1,1] neg_lo:[0,0,1] neg_hi:[0,0,1]
	v_pk_fma_f32 v[62:63], v[62:63], v[156:157], v[34:35] op_sel_hi:[1,0,1]
	v_pk_mul_f32 v[34:35], v[170:171], v[28:29] op_sel:[1,0]
	v_pk_fma_f32 v[30:31], v[198:199], v[2:3], 0 op_sel_hi:[0,1,0]
	v_pk_fma_f32 v[34:35], v[178:179], v[70:71], v[34:35] op_sel:[1,0,0] neg_lo:[0,0,1] neg_hi:[0,0,1]
	v_pk_fma_f32 v[60:61], v[60:61], v[156:157], v[34:35] op_sel:[0,1,0]
	v_pk_mul_f32 v[34:35], v[172:173], v[28:29] op_sel_hi:[0,1]
	v_pk_fma_f32 v[30:31], v[200:201], v[66:67], v[30:31] op_sel_hi:[0,1,1]
	v_pk_fma_f32 v[34:35], v[180:181], v[70:71], v[34:35] op_sel_hi:[0,1,1] neg_lo:[0,0,1] neg_hi:[0,0,1]
	v_pk_mul_f32 v[28:29], v[172:173], v[28:29] op_sel:[1,0]
	v_pk_fma_f32 v[30:31], v[202:203], v[62:63], v[30:31] op_sel_hi:[0,1,1]
	v_pk_fma_f32 v[46:47], v[46:47], v[158:159], v[34:35] op_sel_hi:[1,0,1]
	v_pk_fma_f32 v[28:29], v[180:181], v[70:71], v[28:29] op_sel:[1,0,0] neg_lo:[0,0,1] neg_hi:[0,0,1]
	v_pk_fma_f32 v[32:33], v[202:203], v[60:61], v[32:33] op_sel:[1,0,0]
	v_pk_fma_f32 v[44:45], v[44:45], v[158:159], v[28:29] op_sel:[0,1,0]
	v_pk_fma_f32 v[28:29], v[204:205], v[46:47], v[30:31] op_sel_hi:[0,1,1]
	v_pk_fma_f32 v[30:31], v[204:205], v[44:45], v[32:33] op_sel:[1,0,0]
	v_pk_add_f32 v[28:29], v[28:29], v[30:31]
	s_nop 1
	v_mov_b32_dpp v30, v28 quad_perm:[1,0,3,2] row_mask:0xf bank_mask:0xf bound_ctrl:1
	v_mov_b32_dpp v31, v29 quad_perm:[1,0,3,2] row_mask:0xf bank_mask:0xf bound_ctrl:1
	v_pk_add_f32 v[28:29], v[28:29], v[30:31]
	s_nop 1
	v_mov_b32_dpp v30, v28 quad_perm:[2,3,0,1] row_mask:0xf bank_mask:0xf bound_ctrl:1
	v_mov_b32_dpp v31, v29 quad_perm:[2,3,0,1] row_mask:0xf bank_mask:0xf bound_ctrl:1
	v_pk_add_f32 v[28:29], v[28:29], v[30:31]
	s_nop 1
	v_mov_b32_dpp v30, v28 row_half_mirror row_mask:0xf bank_mask:0xf bound_ctrl:1
	v_mov_b32_dpp v31, v29 row_half_mirror row_mask:0xf bank_mask:0xf bound_ctrl:1
	s_and_saveexec_b64 s[20:21], s[14:15]
	v_pk_add_f32 v[28:29], v[28:29], v[30:31]
	ds_write_b64 v72, v[28:29] offset:52480
	s_or_b64 exec, exec, s[20:21]
	ds_read_b128 v[152:155], v1 offset:7680
	ds_read_b128 v[156:159], v1 offset:7696
	ds_read_b128 v[166:169], v1 offset:11776
	ds_read_b128 v[170:173], v1 offset:11792
	ds_read_b128 v[174:177], v1 offset:15872
	ds_read_b128 v[178:181], v1 offset:15888
	ds_read_b128 v[198:201], v1 offset:19968
	ds_read_b128 v[202:205], v1 offset:19984
	ds_read_b64 v[70:71], v73 offset:24064
	ds_read_b128 v[32:35], v74 offset:3840
	ds_read_b128 v[28:31], v74 offset:3856
	s_waitcnt lgkmcnt(12)
	v_pk_mul_f32 v[74:75], v[42:43], v[66:67] op_sel_hi:[0,1]
	v_pk_fma_f32 v[74:75], v[40:41], v[2:3], v[74:75] op_sel_hi:[0,1,1]
	v_pk_mul_f32 v[42:43], v[42:43], v[64:65] op_sel:[1,0]
	v_pk_fma_f32 v[40:41], v[40:41], v[68:69], v[42:43] op_sel:[1,0,0]
	s_waitcnt lgkmcnt(11)
	v_pk_fma_f32 v[42:43], v[36:37], v[62:63], v[74:75] op_sel_hi:[0,1,1]
	v_pk_fma_f32 v[36:37], v[36:37], v[60:61], v[40:41] op_sel:[1,0,0]
	v_pk_fma_f32 v[40:41], v[38:39], v[46:47], v[42:43] op_sel_hi:[0,1,1]
	v_pk_fma_f32 v[36:37], v[38:39], v[44:45], v[36:37] op_sel:[1,0,0]
	v_pk_add_f32 v[36:37], v[40:41], v[36:37]
	s_waitcnt lgkmcnt(10)
	v_mov_b32_dpp v38, v36 quad_perm:[1,0,3,2] row_mask:0xf bank_mask:0xf bound_ctrl:1
	v_mov_b32_dpp v39, v37 quad_perm:[1,0,3,2] row_mask:0xf bank_mask:0xf bound_ctrl:1
	v_pk_add_f32 v[36:37], v[36:37], v[38:39]
	s_nop 1
	v_mov_b32_dpp v38, v36 quad_perm:[2,3,0,1] row_mask:0xf bank_mask:0xf bound_ctrl:1
	v_mov_b32_dpp v39, v37 quad_perm:[2,3,0,1] row_mask:0xf bank_mask:0xf bound_ctrl:1
	v_pk_add_f32 v[36:37], v[36:37], v[38:39]
	s_nop 1
	v_mov_b32_dpp v38, v36 row_half_mirror row_mask:0xf bank_mask:0xf bound_ctrl:1
	v_mov_b32_dpp v39, v37 row_half_mirror row_mask:0xf bank_mask:0xf bound_ctrl:1
	v_pk_add_f32 v[74:75], v[36:37], v[38:39]
	s_waitcnt lgkmcnt(8)
	v_pk_mul_f32 v[36:37], v[166:167], v[74:75] op_sel_hi:[0,1]
	s_waitcnt lgkmcnt(2)
	v_pk_fma_f32 v[36:37], v[174:175], v[70:71], v[36:37] op_sel_hi:[0,1,1] neg_lo:[0,0,1] neg_hi:[0,0,1]
	v_pk_mul_f32 v[38:39], v[168:169], v[74:75] op_sel_hi:[0,1]
	v_pk_fma_f32 v[2:3], v[2:3], v[152:153], v[36:37] op_sel_hi:[1,0,1]
	v_pk_mul_f32 v[36:37], v[166:167], v[74:75] op_sel:[1,0]
	v_pk_fma_f32 v[38:39], v[176:177], v[70:71], v[38:39] op_sel_hi:[0,1,1] neg_lo:[0,0,1] neg_hi:[0,0,1]
	v_pk_fma_f32 v[36:37], v[174:175], v[70:71], v[36:37] op_sel:[1,0,0] neg_lo:[0,0,1] neg_hi:[0,0,1]
	v_pk_fma_f32 v[38:39], v[66:67], v[154:155], v[38:39] op_sel_hi:[1,0,1]
	v_pk_fma_f32 v[36:37], v[68:69], v[152:153], v[36:37] op_sel:[0,1,0]
	v_pk_mul_f32 v[66:67], v[168:169], v[74:75] op_sel:[1,0]
	v_pk_fma_f32 v[42:43], v[198:199], v[2:3], 0 op_sel_hi:[0,1,0]
	v_pk_fma_f32 v[66:67], v[176:177], v[70:71], v[66:67] op_sel:[1,0,0] neg_lo:[0,0,1] neg_hi:[0,0,1]
	v_pk_fma_f32 v[68:69], v[198:199], v[36:37], 0 op_sel:[1,0,0] op_sel_hi:[1,1,0]
	v_pk_fma_f32 v[40:41], v[64:65], v[154:155], v[66:67] op_sel:[0,1,0]
	v_pk_fma_f32 v[64:65], v[200:201], v[38:39], v[42:43] op_sel_hi:[0,1,1]
	v_pk_fma_f32 v[66:67], v[200:201], v[40:41], v[68:69] op_sel:[1,0,0]
	v_pk_mul_f32 v[42:43], v[170:171], v[74:75] op_sel_hi:[0,1]
	v_pk_fma_f32 v[42:43], v[178:179], v[70:71], v[42:43] op_sel_hi:[0,1,1] neg_lo:[0,0,1] neg_hi:[0,0,1]
	v_pk_fma_f32 v[42:43], v[62:63], v[156:157], v[42:43] op_sel_hi:[1,0,1]
	v_pk_mul_f32 v[62:63], v[170:171], v[74:75] op_sel:[1,0]
	v_pk_fma_f32 v[62:63], v[178:179], v[70:71], v[62:63] op_sel:[1,0,0] neg_lo:[0,0,1] neg_hi:[0,0,1]
	v_pk_fma_f32 v[60:61], v[60:61], v[156:157], v[62:63] op_sel:[0,1,0]
	v_pk_fma_f32 v[62:63], v[202:203], v[42:43], v[64:65] op_sel_hi:[0,1,1]
	v_pk_fma_f32 v[64:65], v[202:203], v[60:61], v[66:67] op_sel:[1,0,0]
	v_pk_mul_f32 v[66:67], v[172:173], v[74:75] op_sel_hi:[0,1]
	v_pk_fma_f32 v[66:67], v[180:181], v[70:71], v[66:67] op_sel_hi:[0,1,1] neg_lo:[0,0,1] neg_hi:[0,0,1]
	v_pk_mul_f32 v[68:69], v[172:173], v[74:75] op_sel:[1,0]
	v_pk_fma_f32 v[46:47], v[46:47], v[158:159], v[66:67] op_sel_hi:[1,0,1]
	v_pk_fma_f32 v[68:69], v[180:181], v[70:71], v[68:69] op_sel:[1,0,0] neg_lo:[0,0,1] neg_hi:[0,0,1]
	v_pk_fma_f32 v[44:45], v[44:45], v[158:159], v[68:69] op_sel:[0,1,0]
	v_pk_fma_f32 v[62:63], v[204:205], v[46:47], v[62:63] op_sel_hi:[0,1,1]
	v_pk_fma_f32 v[64:65], v[204:205], v[44:45], v[64:65] op_sel:[1,0,0]
	v_pk_add_f32 v[62:63], v[62:63], v[64:65]
	s_nop 1
	v_mov_b32_dpp v64, v62 quad_perm:[1,0,3,2] row_mask:0xf bank_mask:0xf bound_ctrl:1
	v_mov_b32_dpp v65, v63 quad_perm:[1,0,3,2] row_mask:0xf bank_mask:0xf bound_ctrl:1
	v_pk_add_f32 v[62:63], v[62:63], v[64:65]
	s_nop 1
	v_mov_b32_dpp v64, v62 quad_perm:[2,3,0,1] row_mask:0xf bank_mask:0xf bound_ctrl:1
	v_mov_b32_dpp v65, v63 quad_perm:[2,3,0,1] row_mask:0xf bank_mask:0xf bound_ctrl:1
	v_pk_add_f32 v[62:63], v[62:63], v[64:65]
	s_nop 1
	v_mov_b32_dpp v64, v62 row_half_mirror row_mask:0xf bank_mask:0xf bound_ctrl:1
	v_mov_b32_dpp v65, v63 row_half_mirror row_mask:0xf bank_mask:0xf bound_ctrl:1
	s_and_saveexec_b64 s[20:21], s[14:15]
	v_pk_add_f32 v[62:63], v[62:63], v[64:65]
	ds_write_b64 v72, v[62:63] offset:52736
	s_or_b64 exec, exec, s[20:21]
	s_waitcnt lgkmcnt(1)
	v_pk_mul_f32 v[66:67], v[34:35], v[38:39] op_sel_hi:[0,1]
	v_pk_mul_f32 v[68:69], v[34:35], v[40:41] op_sel:[1,0]
	v_pk_fma_f32 v[66:67], v[32:33], v[2:3], v[66:67] op_sel_hi:[0,1,1]
	v_pk_fma_f32 v[68:69], v[32:33], v[36:37], v[68:69] op_sel:[1,0,0]
	s_waitcnt lgkmcnt(0)
	v_pk_fma_f32 v[66:67], v[28:29], v[42:43], v[66:67] op_sel_hi:[0,1,1]
	v_pk_fma_f32 v[68:69], v[28:29], v[60:61], v[68:69] op_sel:[1,0,0]
	v_pk_fma_f32 v[66:67], v[30:31], v[46:47], v[66:67] op_sel_hi:[0,1,1]
	v_pk_fma_f32 v[68:69], v[30:31], v[44:45], v[68:69] op_sel:[1,0,0]
	v_pk_add_f32 v[66:67], v[66:67], v[68:69]
	ds_read_b64 v[74:75], v73 offset:24320
	ds_read_b128 v[152:155], v1 offset:20240
	ds_read_b128 v[156:159], v1 offset:20224
	ds_read_b128 v[166:169], v1 offset:16144
	ds_read_b128 v[62:65], v1 offset:16128
	ds_read_b128 v[170:173], v1 offset:12048
	ds_read_b128 v[174:177], v1 offset:12032
	ds_read_b128 v[178:181], v1 offset:7936
	ds_read_b128 v[198:201], v1 offset:7952
	v_mov_b32_dpp v68, v66 quad_perm:[1,0,3,2] row_mask:0xf bank_mask:0xf bound_ctrl:1
	v_mov_b32_dpp v69, v67 quad_perm:[1,0,3,2] row_mask:0xf bank_mask:0xf bound_ctrl:1
	v_pk_add_f32 v[66:67], v[66:67], v[68:69]
	s_nop 1
	v_mov_b32_dpp v68, v66 quad_perm:[2,3,0,1] row_mask:0xf bank_mask:0xf bound_ctrl:1
	v_mov_b32_dpp v69, v67 quad_perm:[2,3,0,1] row_mask:0xf bank_mask:0xf bound_ctrl:1
	v_pk_add_f32 v[66:67], v[66:67], v[68:69]
	s_nop 1
	v_mov_b32_dpp v68, v66 row_half_mirror row_mask:0xf bank_mask:0xf bound_ctrl:1
	v_mov_b32_dpp v69, v67 row_half_mirror row_mask:0xf bank_mask:0xf bound_ctrl:1
	v_pk_add_f32 v[160:161], v[66:67], v[68:69]
	s_waitcnt lgkmcnt(2)
	v_pk_mul_f32 v[66:67], v[174:175], v[160:161] op_sel_hi:[0,1]
	v_pk_fma_f32 v[66:67], v[74:75], v[62:63], v[66:67] op_sel_hi:[1,0,1] neg_lo:[0,0,1] neg_hi:[0,0,1]
	s_waitcnt lgkmcnt(1)
	v_pk_fma_f32 v[70:71], v[2:3], v[178:179], v[66:67] op_sel_hi:[1,0,1]
	v_pk_mul_f32 v[2:3], v[174:175], v[160:161] op_sel:[1,0]
	s_nop 0
	v_pk_fma_f32 v[2:3], v[74:75], v[62:63], v[2:3] op_sel:[0,1,0] neg_lo:[0,0,1] neg_hi:[0,0,1]
	v_pk_mul_f32 v[62:63], v[176:177], v[160:161] op_sel_hi:[0,1]
	v_pk_fma_f32 v[62:63], v[74:75], v[64:65], v[62:63] op_sel_hi:[1,0,1] neg_lo:[0,0,1] neg_hi:[0,0,1]
	v_pk_fma_f32 v[66:67], v[38:39], v[180:181], v[62:63] op_sel_hi:[1,0,1]
	v_pk_mul_f32 v[62:63], v[176:177], v[160:161] op_sel:[1,0]
	v_pk_fma_f32 v[68:69], v[36:37], v[178:179], v[2:3] op_sel:[0,1,0]
	v_pk_fma_f32 v[62:63], v[74:75], v[64:65], v[62:63] op_sel:[0,1,0] neg_lo:[0,0,1] neg_hi:[0,0,1]
	v_pk_fma_f32 v[36:37], v[156:157], v[68:69], 0 op_sel:[1,0,0] op_sel_hi:[1,1,0]
	v_pk_fma_f32 v[64:65], v[40:41], v[180:181], v[62:63] op_sel:[0,1,0]
	v_pk_fma_f32 v[36:37], v[158:159], v[64:65], v[36:37] op_sel:[1,0,0]
	v_pk_mul_f32 v[38:39], v[170:171], v[160:161] op_sel_hi:[0,1]
	v_pk_fma_f32 v[38:39], v[74:75], v[166:167], v[38:39] op_sel_hi:[1,0,1] neg_lo:[0,0,1] neg_hi:[0,0,1]
	s_waitcnt lgkmcnt(0)
	v_pk_fma_f32 v[62:63], v[42:43], v[198:199], v[38:39] op_sel_hi:[1,0,1]
	v_pk_mul_f32 v[38:39], v[170:171], v[160:161] op_sel:[1,0]
	v_pk_fma_f32 v[2:3], v[156:157], v[70:71], 0 op_sel_hi:[0,1,0]
	v_pk_fma_f32 v[38:39], v[74:75], v[166:167], v[38:39] op_sel:[0,1,0] neg_lo:[0,0,1] neg_hi:[0,0,1]
	v_mov_b32_e32 v42, v169
	v_pk_fma_f32 v[60:61], v[60:61], v[198:199], v[38:39] op_sel:[0,1,0]
	v_pk_mul_f32 v[38:39], v[172:173], v[160:161] op_sel_hi:[0,1]
	v_pk_fma_f32 v[38:39], v[74:75], v[168:169], v[38:39] op_sel_hi:[1,0,1] neg_lo:[0,0,1] neg_hi:[0,0,1]
	v_pk_mul_f32 v[40:41], v[172:173], v[160:161] op_sel:[1,0]
	v_pk_fma_f32 v[2:3], v[158:159], v[66:67], v[2:3] op_sel_hi:[0,1,1]
	v_pk_fma_f32 v[46:47], v[46:47], v[200:201], v[38:39] op_sel_hi:[1,0,1]
	v_pk_fma_f32 v[40:41], v[74:75], v[42:43], v[40:41] op_sel_hi:[1,0,1] neg_lo:[0,0,1] neg_hi:[0,0,1]
	v_pk_fma_f32 v[2:3], v[152:153], v[62:63], v[2:3] op_sel_hi:[0,1,1]
	v_pk_fma_f32 v[36:37], v[152:153], v[60:61], v[36:37] op_sel:[1,0,0]
	v_pk_fma_f32 v[44:45], v[44:45], v[200:201], v[40:41] op_sel:[0,1,0]
	v_mov_b32_e32 v38, v155
	v_pk_fma_f32 v[2:3], v[154:155], v[46:47], v[2:3] op_sel_hi:[0,1,1]
	v_pk_fma_f32 v[36:37], v[38:39], v[44:45], v[36:37] op_sel_hi:[0,1,1]
	v_pk_add_f32 v[2:3], v[2:3], v[36:37]
	s_nop 1
	v_mov_b32_dpp v36, v2 quad_perm:[1,0,3,2] row_mask:0xf bank_mask:0xf bound_ctrl:1
	v_mov_b32_dpp v37, v3 quad_perm:[1,0,3,2] row_mask:0xf bank_mask:0xf bound_ctrl:1
	v_pk_add_f32 v[2:3], v[2:3], v[36:37]
	s_nop 1
	v_mov_b32_dpp v36, v2 quad_perm:[2,3,0,1] row_mask:0xf bank_mask:0xf bound_ctrl:1
	v_mov_b32_dpp v37, v3 quad_perm:[2,3,0,1] row_mask:0xf bank_mask:0xf bound_ctrl:1
	v_pk_add_f32 v[2:3], v[2:3], v[36:37]
	s_nop 1
	v_mov_b32_dpp v36, v2 row_half_mirror row_mask:0xf bank_mask:0xf bound_ctrl:1
	v_mov_b32_dpp v37, v3 row_half_mirror row_mask:0xf bank_mask:0xf bound_ctrl:1
	s_and_saveexec_b64 s[20:21], s[14:15]
	s_cbranch_execz .LBB0_575
	v_pk_add_f32 v[2:3], v[2:3], v[36:37]
	ds_write_b64 v72, v[2:3] offset:52992
	s_branch .LBB0_575
